# phase D (compression MLP layer 2) moved from per-row VALU fma with 256 weight loads per row to the f32 matrix cores (v_mfma_f32_16x16x4_f32, f32 in/acc): 16-row wave-tasks, weights read once per task
# speedup vs baseline: 1.0178x; 1.0159x over previous
; #define INP(k) ({ int k_ = (k); LAUNDER_S(k_); (const float*)(const GAS float*)P.in[k_]; })
; __global__ void __launch_bounds__(512, 2) hybrid_fwd(Params P) {
;     ...
;         { PHASE_BEGIN
;             const int gwave = bx * 8 + wave, nwaves = G * 8;
;             const float* cw2 = INP(10) + (size_t)L * 2 * 256 * 64; const float* nkn = INP(7) + L * 192;
;             bf16_t* KC = (bf16_t*)(ws + WS_KC); bf16_t* VCT = (bf16_t*)(ws + WS_VCT);
;             for (int row = gwave; row < 8192; row += nwaves) { const int kv = row >> 12, rr = row & 4095, bg = rr >> 9, n = rr & 511;
;                 f32x4 hv = *(const f32x4*)((const float*)(ws + WS_SMALL) + kv * 256 + 4 * lane);
;                 { const float* pp = (const float*)(ws + WS_H) + ((size_t)(kv * 4) * 4096 + rr) * 256 + 4 * lane;
; #pragma unroll
;                     for (int ks = 0; ks < 4; ++ks) hv += *(const f32x4*)(pp + (size_t)ks * 4096 * 256);
.LBB0_777:
	s_or_b64 exec, exec, s[4:5]
	v_readlane_b32 s4, v255, 17
	s_mov_b32 s6, s4
	s_mov_b64 s[4:5], s[58:59]
	s_mov_b32 s14, s69
	s_mov_b32 s15, s2
	v_mov_b32_e32 v0, v146
	s_barrier
	v_readfirstlane_b32 s7, v0
	s_lshr_b32 s7, s7, 6
	s_cmp_gt_u32 s7, 1
	s_cbranch_scc1 .LBB0_784
	s_load_dwordx2 s[10:11], s[0:1], 0x50
	s_load_dwordx2 s[12:13], s[0:1], 0x38
	s_lshl_b32 s8, s15, 1
	s_add_u32 s8, s8, s7
	s_lshr_b32 s9, s8, 8
	s_and_b32 s8, s8, 0xff
	s_lshl_b32 s8, s8, 4
	v_and_b32_e32 v244, 63, v0
	v_and_b32_e32 v245, 15, v244
	v_lshrrev_b32_e32 v246, 4, v244
	v_lshlrev_b32_e32 v248, 8, v246
	v_lshl_add_u32 v247, v245, 10, v248
	v_lshlrev_b32_e32 v250, 4, v245
	v_lshl_add_u32 v249, v246, 14, v250
	v_lshlrev_b32_e32 v251, 3, v245
	v_lshl_add_u32 v251, v246, 9, v251
	v_lshlrev_b32_e32 v252, 3, v246
	v_lshl_add_u32 v252, v245, 12, v252
	s_lshl_b32 s16, s9, 10
	s_add_u32 s16, s16, 0x2400000
	s_add_u32 s98, s4, s16
	s_addc_u32 s99, s5, 0
	s_lshl_b32 s16, s9, 24
	s_lshl_b32 s18, s8, 10
	s_add_u32 s16, s16, s18
	s_add_u32 s16, s16, 0x3100000
	s_add_u32 s14, s4, s16
	s_addc_u32 s15, s5, 0
	s_waitcnt lgkmcnt(0)
	s_lshl_b32 s16, s6, 17
	s_lshl_b32 s18, s9, 16
	s_add_u32 s16, s16, s18
	s_add_u32 s10, s10, s16
	s_addc_u32 s11, s11, 0
	s_mul_i32 s16, s6, 0x300
	s_add_u32 s12, s12, s16
	s_addc_u32 s13, s13, 0
	global_load_dwordx4 v[240:243], v250, s[12:13]
	global_load_dwordx4 v[0:3], v248, s[98:99]
	global_load_dwordx4 v[4:7], v248, s[98:99] offset:16
	global_load_dwordx4 v[8:11], v248, s[98:99] offset:32
	global_load_dwordx4 v[12:15], v248, s[98:99] offset:48
	global_load_dwordx4 v[16:19], v248, s[98:99] offset:64
	global_load_dwordx4 v[20:23], v248, s[98:99] offset:80
	global_load_dwordx4 v[24:27], v248, s[98:99] offset:96
	global_load_dwordx4 v[28:31], v248, s[98:99] offset:112
	global_load_dwordx4 v[32:35], v248, s[98:99] offset:128
	global_load_dwordx4 v[36:39], v248, s[98:99] offset:144
	global_load_dwordx4 v[40:43], v248, s[98:99] offset:160
	global_load_dwordx4 v[44:47], v248, s[98:99] offset:176
	global_load_dwordx4 v[48:51], v248, s[98:99] offset:192
	global_load_dwordx4 v[52:55], v248, s[98:99] offset:208
	global_load_dwordx4 v[56:59], v248, s[98:99] offset:224
	global_load_dwordx4 v[60:63], v248, s[98:99] offset:240
	global_load_dwordx4 v[82:85], v247, s[14:15]
	global_load_dwordx4 v[86:89], v247, s[14:15] offset:16
	global_load_dwordx4 v[90:93], v247, s[14:15] offset:32
	global_load_dwordx4 v[94:97], v247, s[14:15] offset:48
	global_load_dwordx4 v[98:101], v247, s[14:15] offset:64
	global_load_dwordx4 v[102:105], v247, s[14:15] offset:80
	global_load_dwordx4 v[106:109], v247, s[14:15] offset:96
	global_load_dwordx4 v[110:113], v247, s[14:15] offset:112
	global_load_dwordx4 v[114:117], v247, s[14:15] offset:128
	global_load_dwordx4 v[118:121], v247, s[14:15] offset:144
	global_load_dwordx4 v[122:125], v247, s[14:15] offset:160
	global_load_dwordx4 v[126:129], v247, s[14:15] offset:176
	global_load_dwordx4 v[130:133], v247, s[14:15] offset:192
	global_load_dwordx4 v[134:137], v247, s[14:15] offset:208
	global_load_dwordx4 v[138:141], v247, s[14:15] offset:224
	global_load_dwordx4 v[142:145], v247, s[14:15] offset:240
	s_add_u32 s14, s14, 0x400000
	s_addc_u32 s15, s15, 0
	global_load_dwordx4 v[64:67], v247, s[14:15]
	global_load_dwordx4 v[68:71], v247, s[14:15] offset:16
	global_load_dwordx4 v[72:75], v247, s[14:15] offset:32
	global_load_dwordx4 v[76:79], v247, s[14:15] offset:48
	global_load_dwordx4 v[152:155], v247, s[14:15] offset:64
	global_load_dwordx4 v[156:159], v247, s[14:15] offset:80
	global_load_dwordx4 v[160:163], v247, s[14:15] offset:96
	global_load_dwordx4 v[170:173], v247, s[14:15] offset:112
	global_load_dwordx4 v[174:177], v247, s[14:15] offset:128
	global_load_dwordx4 v[178:181], v247, s[14:15] offset:144
	global_load_dwordx4 v[182:185], v247, s[14:15] offset:160
	global_load_dwordx4 v[220:223], v247, s[14:15] offset:176
	global_load_dwordx4 v[224:227], v247, s[14:15] offset:192
	global_load_dwordx4 v[228:231], v247, s[14:15] offset:208
	global_load_dwordx4 v[232:235], v247, s[14:15] offset:224
	global_load_dwordx4 v[236:239], v247, s[14:15] offset:240
	s_add_u32 s14, s14, 0x400000
	s_addc_u32 s15, s15, 0
	s_waitcnt vmcnt(0)
	v_pk_add_f32 v[0:1], v[0:1], v[82:83]
	v_pk_add_f32 v[2:3], v[2:3], v[84:85]
	v_pk_add_f32 v[4:5], v[4:5], v[86:87]
	v_pk_add_f32 v[6:7], v[6:7], v[88:89]
	v_pk_add_f32 v[8:9], v[8:9], v[90:91]
	v_pk_add_f32 v[10:11], v[10:11], v[92:93]
	v_pk_add_f32 v[12:13], v[12:13], v[94:95]
	v_pk_add_f32 v[14:15], v[14:15], v[96:97]
	v_pk_add_f32 v[16:17], v[16:17], v[98:99]
	v_pk_add_f32 v[18:19], v[18:19], v[100:101]
	v_pk_add_f32 v[20:21], v[20:21], v[102:103]
	v_pk_add_f32 v[22:23], v[22:23], v[104:105]
	v_pk_add_f32 v[24:25], v[24:25], v[106:107]
	v_pk_add_f32 v[26:27], v[26:27], v[108:109]
	v_pk_add_f32 v[28:29], v[28:29], v[110:111]
	v_pk_add_f32 v[30:31], v[30:31], v[112:113]
	v_pk_add_f32 v[32:33], v[32:33], v[114:115]
	v_pk_add_f32 v[34:35], v[34:35], v[116:117]
	v_pk_add_f32 v[36:37], v[36:37], v[118:119]
	v_pk_add_f32 v[38:39], v[38:39], v[120:121]
	v_pk_add_f32 v[40:41], v[40:41], v[122:123]
	v_pk_add_f32 v[42:43], v[42:43], v[124:125]
	v_pk_add_f32 v[44:45], v[44:45], v[126:127]
	v_pk_add_f32 v[46:47], v[46:47], v[128:129]
	v_pk_add_f32 v[48:49], v[48:49], v[130:131]
	v_pk_add_f32 v[50:51], v[50:51], v[132:133]
	v_pk_add_f32 v[52:53], v[52:53], v[134:135]
	v_pk_add_f32 v[54:55], v[54:55], v[136:137]
	v_pk_add_f32 v[56:57], v[56:57], v[138:139]
	v_pk_add_f32 v[58:59], v[58:59], v[140:141]
	v_pk_add_f32 v[60:61], v[60:61], v[142:143]
	v_pk_add_f32 v[62:63], v[62:63], v[144:145]
; __global__ void __launch_bounds__(512, 2) hybrid_fwd(Params P) {
;     ...
;                 { const float* pp = (const float*)(ws + WS_H) + ((size_t)(kv * 4) * 4096 + rr) * 256 + 4 * lane;
; #pragma unroll
;                     for (int ks = 0; ks < 4; ++ks) hv += *(const f32x4*)(pp + (size_t)ks * 4096 * 256);
	v_pk_add_f32 v[0:1], v[0:1], v[64:65]
	v_pk_add_f32 v[2:3], v[2:3], v[66:67]
	v_pk_add_f32 v[4:5], v[4:5], v[68:69]
	v_pk_add_f32 v[6:7], v[6:7], v[70:71]
	v_pk_add_f32 v[8:9], v[8:9], v[72:73]
	v_pk_add_f32 v[10:11], v[10:11], v[74:75]
	v_pk_add_f32 v[12:13], v[12:13], v[76:77]
	v_pk_add_f32 v[14:15], v[14:15], v[78:79]
	v_pk_add_f32 v[16:17], v[16:17], v[152:153]
	v_pk_add_f32 v[18:19], v[18:19], v[154:155]
	v_pk_add_f32 v[20:21], v[20:21], v[156:157]
	v_pk_add_f32 v[22:23], v[22:23], v[158:159]
	v_pk_add_f32 v[24:25], v[24:25], v[160:161]
	v_pk_add_f32 v[26:27], v[26:27], v[162:163]
	v_pk_add_f32 v[28:29], v[28:29], v[170:171]
	v_pk_add_f32 v[30:31], v[30:31], v[172:173]
	v_pk_add_f32 v[32:33], v[32:33], v[174:175]
	v_pk_add_f32 v[34:35], v[34:35], v[176:177]
	v_pk_add_f32 v[36:37], v[36:37], v[178:179]
	v_pk_add_f32 v[38:39], v[38:39], v[180:181]
	v_pk_add_f32 v[40:41], v[40:41], v[182:183]
	v_pk_add_f32 v[42:43], v[42:43], v[184:185]
	v_pk_add_f32 v[44:45], v[44:45], v[220:221]
	v_pk_add_f32 v[46:47], v[46:47], v[222:223]
	v_pk_add_f32 v[48:49], v[48:49], v[224:225]
	v_pk_add_f32 v[50:51], v[50:51], v[226:227]
	v_pk_add_f32 v[52:53], v[52:53], v[228:229]
	v_pk_add_f32 v[54:55], v[54:55], v[230:231]
	v_pk_add_f32 v[56:57], v[56:57], v[232:233]
	v_pk_add_f32 v[58:59], v[58:59], v[234:235]
	v_pk_add_f32 v[60:61], v[60:61], v[236:237]
	v_pk_add_f32 v[62:63], v[62:63], v[238:239]
	global_load_dwordx4 v[82:85], v247, s[14:15]
	global_load_dwordx4 v[86:89], v247, s[14:15] offset:16
	global_load_dwordx4 v[90:93], v247, s[14:15] offset:32
	global_load_dwordx4 v[94:97], v247, s[14:15] offset:48
	global_load_dwordx4 v[98:101], v247, s[14:15] offset:64
	global_load_dwordx4 v[102:105], v247, s[14:15] offset:80
	global_load_dwordx4 v[106:109], v247, s[14:15] offset:96
	global_load_dwordx4 v[110:113], v247, s[14:15] offset:112
	global_load_dwordx4 v[114:117], v247, s[14:15] offset:128
	global_load_dwordx4 v[118:121], v247, s[14:15] offset:144
	global_load_dwordx4 v[122:125], v247, s[14:15] offset:160
	global_load_dwordx4 v[126:129], v247, s[14:15] offset:176
	global_load_dwordx4 v[130:133], v247, s[14:15] offset:192
	global_load_dwordx4 v[134:137], v247, s[14:15] offset:208
	global_load_dwordx4 v[138:141], v247, s[14:15] offset:224
	global_load_dwordx4 v[142:145], v247, s[14:15] offset:240
	s_add_u32 s14, s14, 0x400000
	s_addc_u32 s15, s15, 0
	global_load_dwordx4 v[64:67], v247, s[14:15]
	global_load_dwordx4 v[68:71], v247, s[14:15] offset:16
	global_load_dwordx4 v[72:75], v247, s[14:15] offset:32
	global_load_dwordx4 v[76:79], v247, s[14:15] offset:48
	global_load_dwordx4 v[152:155], v247, s[14:15] offset:64
	global_load_dwordx4 v[156:159], v247, s[14:15] offset:80
	global_load_dwordx4 v[160:163], v247, s[14:15] offset:96
	global_load_dwordx4 v[170:173], v247, s[14:15] offset:112
	global_load_dwordx4 v[174:177], v247, s[14:15] offset:128
	global_load_dwordx4 v[178:181], v247, s[14:15] offset:144
	global_load_dwordx4 v[182:185], v247, s[14:15] offset:160
	global_load_dwordx4 v[220:223], v247, s[14:15] offset:176
	global_load_dwordx4 v[224:227], v247, s[14:15] offset:192
	global_load_dwordx4 v[228:231], v247, s[14:15] offset:208
	global_load_dwordx4 v[232:235], v247, s[14:15] offset:224
	global_load_dwordx4 v[236:239], v247, s[14:15] offset:240
	s_waitcnt vmcnt(0)
	v_pk_add_f32 v[0:1], v[0:1], v[82:83]
	v_pk_add_f32 v[2:3], v[2:3], v[84:85]
	v_pk_add_f32 v[4:5], v[4:5], v[86:87]
	v_pk_add_f32 v[6:7], v[6:7], v[88:89]
	v_pk_add_f32 v[8:9], v[8:9], v[90:91]
	v_pk_add_f32 v[10:11], v[10:11], v[92:93]
	v_pk_add_f32 v[12:13], v[12:13], v[94:95]
	v_pk_add_f32 v[14:15], v[14:15], v[96:97]
	v_pk_add_f32 v[16:17], v[16:17], v[98:99]
	v_pk_add_f32 v[18:19], v[18:19], v[100:101]
	v_pk_add_f32 v[20:21], v[20:21], v[102:103]
	v_pk_add_f32 v[22:23], v[22:23], v[104:105]
	v_pk_add_f32 v[24:25], v[24:25], v[106:107]
	v_pk_add_f32 v[26:27], v[26:27], v[108:109]
	v_pk_add_f32 v[28:29], v[28:29], v[110:111]
	v_pk_add_f32 v[30:31], v[30:31], v[112:113]
	v_pk_add_f32 v[32:33], v[32:33], v[114:115]
	v_pk_add_f32 v[34:35], v[34:35], v[116:117]
	v_pk_add_f32 v[36:37], v[36:37], v[118:119]
	v_pk_add_f32 v[38:39], v[38:39], v[120:121]
	v_pk_add_f32 v[40:41], v[40:41], v[122:123]
	v_pk_add_f32 v[42:43], v[42:43], v[124:125]
	v_pk_add_f32 v[44:45], v[44:45], v[126:127]
	v_pk_add_f32 v[46:47], v[46:47], v[128:129]
	v_pk_add_f32 v[48:49], v[48:49], v[130:131]
	v_pk_add_f32 v[50:51], v[50:51], v[132:133]
	v_pk_add_f32 v[52:53], v[52:53], v[134:135]
	v_pk_add_f32 v[54:55], v[54:55], v[136:137]
	v_pk_add_f32 v[56:57], v[56:57], v[138:139]
	v_pk_add_f32 v[58:59], v[58:59], v[140:141]
	v_pk_add_f32 v[60:61], v[60:61], v[142:143]
	v_pk_add_f32 v[62:63], v[62:63], v[144:145]
	v_pk_add_f32 v[0:1], v[0:1], v[64:65]
	v_pk_add_f32 v[2:3], v[2:3], v[66:67]
	v_pk_add_f32 v[4:5], v[4:5], v[68:69]
	v_pk_add_f32 v[6:7], v[6:7], v[70:71]
	v_pk_add_f32 v[8:9], v[8:9], v[72:73]
	v_pk_add_f32 v[10:11], v[10:11], v[74:75]
	v_pk_add_f32 v[12:13], v[12:13], v[76:77]
	v_pk_add_f32 v[14:15], v[14:15], v[78:79]
	v_pk_add_f32 v[16:17], v[16:17], v[152:153]
	v_pk_add_f32 v[18:19], v[18:19], v[154:155]
	v_pk_add_f32 v[20:21], v[20:21], v[156:157]
	v_pk_add_f32 v[22:23], v[22:23], v[158:159]
	v_pk_add_f32 v[24:25], v[24:25], v[160:161]
	v_pk_add_f32 v[26:27], v[26:27], v[162:163]
	v_pk_add_f32 v[28:29], v[28:29], v[170:171]
	v_pk_add_f32 v[30:31], v[30:31], v[172:173]
	v_pk_add_f32 v[32:33], v[32:33], v[174:175]
	v_pk_add_f32 v[34:35], v[34:35], v[176:177]
	v_pk_add_f32 v[36:37], v[36:37], v[178:179]
	v_pk_add_f32 v[38:39], v[38:39], v[180:181]
	v_pk_add_f32 v[40:41], v[40:41], v[182:183]
; __global__ void __launch_bounds__(512, 2) hybrid_fwd(Params P) {
;     ...
;                     for (int ks = 0; ks < 4; ++ks) hv += *(const f32x4*)(pp + (size_t)ks * 4096 * 256);
; #pragma unroll
;                     for (int e = 0; e < 4; ++e) { const float t = hv[e], z = 0.7978845608028654f * (t + 0.044715f * t * t * t);
;                         const float th = 1.0f - 2.0f * __builtin_amdgcn_rcpf(1.0f + __expf(2.0f * z)); hv[e] = 0.5f * t * (1.0f + th); } }
;                 const float* wp = cw2 + (size_t)kv * 256 * 64 + lane; float a = 0.f;
; #pragma unroll
;                 for (int k = 0; k < 256; ++k) { const float hk = __uint_as_float(__builtin_amdgcn_readlane(__float_as_uint(hv[k & 3]), k >> 2)); a = fmaf(hk, wp[k * 64], a); }
	v_pk_add_f32 v[42:43], v[42:43], v[184:185]
	v_pk_add_f32 v[44:45], v[44:45], v[220:221]
	v_pk_add_f32 v[46:47], v[46:47], v[222:223]
	v_pk_add_f32 v[48:49], v[48:49], v[224:225]
	v_pk_add_f32 v[50:51], v[50:51], v[226:227]
	v_pk_add_f32 v[52:53], v[52:53], v[228:229]
	v_pk_add_f32 v[54:55], v[54:55], v[230:231]
	v_pk_add_f32 v[56:57], v[56:57], v[232:233]
	v_pk_add_f32 v[58:59], v[58:59], v[234:235]
	v_pk_add_f32 v[60:61], v[60:61], v[236:237]
	v_pk_add_f32 v[62:63], v[62:63], v[238:239]
	global_load_dwordx4 v[82:85], v249, s[10:11]
	global_load_dwordx4 v[86:89], v249, s[10:11] offset:256
	global_load_dwordx4 v[90:93], v249, s[10:11] offset:512
	global_load_dwordx4 v[94:97], v249, s[10:11] offset:768
	global_load_dwordx4 v[98:101], v249, s[10:11] offset:1024
	global_load_dwordx4 v[102:105], v249, s[10:11] offset:1280
	global_load_dwordx4 v[106:109], v249, s[10:11] offset:1536
	global_load_dwordx4 v[110:113], v249, s[10:11] offset:1792
	s_add_u32 s10, s10, 0x800
	s_addc_u32 s11, s11, 0
	global_load_dwordx4 v[114:117], v249, s[10:11]
	global_load_dwordx4 v[118:121], v249, s[10:11] offset:256
	global_load_dwordx4 v[122:125], v249, s[10:11] offset:512
	global_load_dwordx4 v[126:129], v249, s[10:11] offset:768
	global_load_dwordx4 v[130:133], v249, s[10:11] offset:1024
	global_load_dwordx4 v[134:137], v249, s[10:11] offset:1280
	global_load_dwordx4 v[138:141], v249, s[10:11] offset:1536
	global_load_dwordx4 v[142:145], v249, s[10:11] offset:1792
	s_add_u32 s10, s10, 0x800
	s_addc_u32 s11, s11, 0
	s_mov_b32 s16, 0x3d372713
	s_mov_b32 s18, 0x40135761
	v_mul_f32_e32 v224, v0, v0
	v_mul_f32_e32 v225, v1, v1
	v_mul_f32_e32 v226, v2, v2
	v_mul_f32_e32 v227, v3, v3
	v_mul_f32_e32 v224, v224, v0
	v_mul_f32_e32 v225, v225, v1
	v_mul_f32_e32 v226, v226, v2
	v_mul_f32_e32 v227, v227, v3
	v_fma_f32 v228, s16, v224, v0
	v_fma_f32 v229, s16, v225, v1
	v_fma_f32 v230, s16, v226, v2
	v_fma_f32 v231, s16, v227, v3
	v_mul_f32_e32 v228, s18, v228
	v_mul_f32_e32 v229, s18, v229
	v_mul_f32_e32 v230, s18, v230
	v_mul_f32_e32 v231, s18, v231
	v_exp_f32_e32 v232, v228
	v_exp_f32_e32 v233, v229
	v_exp_f32_e32 v234, v230
	v_exp_f32_e32 v235, v231
	v_mul_f32_e32 v236, 0.5, v0
	v_mul_f32_e32 v237, 0.5, v1
	v_mul_f32_e32 v238, 0.5, v2
	v_mul_f32_e32 v239, 0.5, v3
	v_add_f32_e32 v232, 1.0, v232
	v_add_f32_e32 v233, 1.0, v233
	v_add_f32_e32 v234, 1.0, v234
	v_add_f32_e32 v235, 1.0, v235
	v_rcp_f32_e32 v232, v232
	v_rcp_f32_e32 v233, v233
	v_rcp_f32_e32 v234, v234
	v_rcp_f32_e32 v235, v235
	s_nop 0
	v_fma_f32 v232, v232, -2.0, 1.0
	v_fma_f32 v233, v233, -2.0, 1.0
	v_fma_f32 v234, v234, -2.0, 1.0
	v_fma_f32 v235, v235, -2.0, 1.0
	v_fma_f32 v0, v236, v232, v236
	v_fma_f32 v1, v237, v233, v237
	v_fma_f32 v2, v238, v234, v238
	v_fma_f32 v3, v239, v235, v239
	v_mul_f32_e32 v224, v4, v4
	v_mul_f32_e32 v225, v5, v5
	v_mul_f32_e32 v226, v6, v6
	v_mul_f32_e32 v227, v7, v7
	v_mul_f32_e32 v224, v224, v4
	v_mul_f32_e32 v225, v225, v5
	v_mul_f32_e32 v226, v226, v6
	v_mul_f32_e32 v227, v227, v7
	v_fma_f32 v228, s16, v224, v4
	v_fma_f32 v229, s16, v225, v5
	v_fma_f32 v230, s16, v226, v6
	v_fma_f32 v231, s16, v227, v7
	v_mul_f32_e32 v228, s18, v228
	v_mul_f32_e32 v229, s18, v229
	v_mul_f32_e32 v230, s18, v230
	v_mul_f32_e32 v231, s18, v231
	v_exp_f32_e32 v232, v228
	v_exp_f32_e32 v233, v229
	v_exp_f32_e32 v234, v230
	v_exp_f32_e32 v235, v231
	v_mul_f32_e32 v236, 0.5, v4
	v_mul_f32_e32 v237, 0.5, v5
	v_mul_f32_e32 v238, 0.5, v6
	v_mul_f32_e32 v239, 0.5, v7
	v_add_f32_e32 v232, 1.0, v232
	v_add_f32_e32 v233, 1.0, v233
	v_add_f32_e32 v234, 1.0, v234
	v_add_f32_e32 v235, 1.0, v235
	v_rcp_f32_e32 v232, v232
	v_rcp_f32_e32 v233, v233
	v_rcp_f32_e32 v234, v234
	v_rcp_f32_e32 v235, v235
	s_nop 0
	v_fma_f32 v232, v232, -2.0, 1.0
	v_fma_f32 v233, v233, -2.0, 1.0
	v_fma_f32 v234, v234, -2.0, 1.0
	v_fma_f32 v235, v235, -2.0, 1.0
	v_fma_f32 v4, v236, v232, v236
	v_fma_f32 v5, v237, v233, v237
	v_fma_f32 v6, v238, v234, v238
	v_fma_f32 v7, v239, v235, v239
	v_mul_f32_e32 v224, v8, v8
	v_mul_f32_e32 v225, v9, v9
	v_mul_f32_e32 v226, v10, v10
	v_mul_f32_e32 v227, v11, v11
	v_mul_f32_e32 v224, v224, v8
	v_mul_f32_e32 v225, v225, v9
	v_mul_f32_e32 v226, v226, v10
	v_mul_f32_e32 v227, v227, v11
	v_fma_f32 v228, s16, v224, v8
	v_fma_f32 v229, s16, v225, v9
	v_fma_f32 v230, s16, v226, v10
	v_fma_f32 v231, s16, v227, v11
	v_mul_f32_e32 v228, s18, v228
	v_mul_f32_e32 v229, s18, v229
	v_mul_f32_e32 v230, s18, v230
	v_mul_f32_e32 v231, s18, v231
	v_exp_f32_e32 v232, v228
	v_exp_f32_e32 v233, v229
	v_exp_f32_e32 v234, v230
	v_exp_f32_e32 v235, v231
	v_mul_f32_e32 v236, 0.5, v8
	v_mul_f32_e32 v237, 0.5, v9
	v_mul_f32_e32 v238, 0.5, v10
	v_mul_f32_e32 v239, 0.5, v11
	v_add_f32_e32 v232, 1.0, v232
	v_add_f32_e32 v233, 1.0, v233
	v_add_f32_e32 v234, 1.0, v234
	v_add_f32_e32 v235, 1.0, v235
	v_rcp_f32_e32 v232, v232
	v_rcp_f32_e32 v233, v233
	v_rcp_f32_e32 v234, v234
	v_rcp_f32_e32 v235, v235
	s_nop 0
	v_fma_f32 v232, v232, -2.0, 1.0
	v_fma_f32 v233, v233, -2.0, 1.0
	v_fma_f32 v234, v234, -2.0, 1.0
	v_fma_f32 v235, v235, -2.0, 1.0
	v_fma_f32 v8, v236, v232, v236
	v_fma_f32 v9, v237, v233, v237
	v_fma_f32 v10, v238, v234, v238
	v_fma_f32 v11, v239, v235, v239
	v_mul_f32_e32 v224, v12, v12
	v_mul_f32_e32 v225, v13, v13
	v_mul_f32_e32 v226, v14, v14
	v_mul_f32_e32 v227, v15, v15
	v_mul_f32_e32 v224, v224, v12
	v_mul_f32_e32 v225, v225, v13
	v_mul_f32_e32 v226, v226, v14
	v_mul_f32_e32 v227, v227, v15
	v_fma_f32 v228, s16, v224, v12
	v_fma_f32 v229, s16, v225, v13
	v_fma_f32 v230, s16, v226, v14
	v_fma_f32 v231, s16, v227, v15
	v_mul_f32_e32 v228, s18, v228
	v_mul_f32_e32 v229, s18, v229
	v_mul_f32_e32 v230, s18, v230
; __global__ void __launch_bounds__(512, 2) hybrid_fwd(Params P) {
;     ...
; #pragma unroll
;                     for (int e = 0; e < 4; ++e) { const float t = hv[e], z = 0.7978845608028654f * (t + 0.044715f * t * t * t);
;                         const float th = 1.0f - 2.0f * __builtin_amdgcn_rcpf(1.0f + __expf(2.0f * z)); hv[e] = 0.5f * t * (1.0f + th); } }
	v_mul_f32_e32 v231, s18, v231
	v_exp_f32_e32 v232, v228
	v_exp_f32_e32 v233, v229
	v_exp_f32_e32 v234, v230
	v_exp_f32_e32 v235, v231
	v_mul_f32_e32 v236, 0.5, v12
	v_mul_f32_e32 v237, 0.5, v13
	v_mul_f32_e32 v238, 0.5, v14
	v_mul_f32_e32 v239, 0.5, v15
	v_add_f32_e32 v232, 1.0, v232
	v_add_f32_e32 v233, 1.0, v233
	v_add_f32_e32 v234, 1.0, v234
	v_add_f32_e32 v235, 1.0, v235
	v_rcp_f32_e32 v232, v232
	v_rcp_f32_e32 v233, v233
	v_rcp_f32_e32 v234, v234
	v_rcp_f32_e32 v235, v235
	s_nop 0
	v_fma_f32 v232, v232, -2.0, 1.0
	v_fma_f32 v233, v233, -2.0, 1.0
	v_fma_f32 v234, v234, -2.0, 1.0
	v_fma_f32 v235, v235, -2.0, 1.0
	v_fma_f32 v12, v236, v232, v236
	v_fma_f32 v13, v237, v233, v237
	v_fma_f32 v14, v238, v234, v238
	v_fma_f32 v15, v239, v235, v239
	v_mul_f32_e32 v224, v16, v16
	v_mul_f32_e32 v225, v17, v17
	v_mul_f32_e32 v226, v18, v18
	v_mul_f32_e32 v227, v19, v19
	v_mul_f32_e32 v224, v224, v16
	v_mul_f32_e32 v225, v225, v17
	v_mul_f32_e32 v226, v226, v18
	v_mul_f32_e32 v227, v227, v19
	v_fma_f32 v228, s16, v224, v16
	v_fma_f32 v229, s16, v225, v17
	v_fma_f32 v230, s16, v226, v18
	v_fma_f32 v231, s16, v227, v19
	v_mul_f32_e32 v228, s18, v228
	v_mul_f32_e32 v229, s18, v229
	v_mul_f32_e32 v230, s18, v230
	v_mul_f32_e32 v231, s18, v231
	v_exp_f32_e32 v232, v228
	v_exp_f32_e32 v233, v229
	v_exp_f32_e32 v234, v230
	v_exp_f32_e32 v235, v231
	v_mul_f32_e32 v236, 0.5, v16
	v_mul_f32_e32 v237, 0.5, v17
	v_mul_f32_e32 v238, 0.5, v18
	v_mul_f32_e32 v239, 0.5, v19
	v_add_f32_e32 v232, 1.0, v232
	v_add_f32_e32 v233, 1.0, v233
	v_add_f32_e32 v234, 1.0, v234
	v_add_f32_e32 v235, 1.0, v235
	v_rcp_f32_e32 v232, v232
	v_rcp_f32_e32 v233, v233
	v_rcp_f32_e32 v234, v234
	v_rcp_f32_e32 v235, v235
	s_nop 0
	v_fma_f32 v232, v232, -2.0, 1.0
	v_fma_f32 v233, v233, -2.0, 1.0
	v_fma_f32 v234, v234, -2.0, 1.0
	v_fma_f32 v235, v235, -2.0, 1.0
	v_fma_f32 v16, v236, v232, v236
	v_fma_f32 v17, v237, v233, v237
	v_fma_f32 v18, v238, v234, v238
	v_fma_f32 v19, v239, v235, v239
	v_mul_f32_e32 v224, v20, v20
	v_mul_f32_e32 v225, v21, v21
	v_mul_f32_e32 v226, v22, v22
	v_mul_f32_e32 v227, v23, v23
	v_mul_f32_e32 v224, v224, v20
	v_mul_f32_e32 v225, v225, v21
	v_mul_f32_e32 v226, v226, v22
	v_mul_f32_e32 v227, v227, v23
	v_fma_f32 v228, s16, v224, v20
	v_fma_f32 v229, s16, v225, v21
	v_fma_f32 v230, s16, v226, v22
	v_fma_f32 v231, s16, v227, v23
	v_mul_f32_e32 v228, s18, v228
	v_mul_f32_e32 v229, s18, v229
	v_mul_f32_e32 v230, s18, v230
	v_mul_f32_e32 v231, s18, v231
	v_exp_f32_e32 v232, v228
	v_exp_f32_e32 v233, v229
	v_exp_f32_e32 v234, v230
	v_exp_f32_e32 v235, v231
	v_mul_f32_e32 v236, 0.5, v20
	v_mul_f32_e32 v237, 0.5, v21
	v_mul_f32_e32 v238, 0.5, v22
	v_mul_f32_e32 v239, 0.5, v23
	v_add_f32_e32 v232, 1.0, v232
	v_add_f32_e32 v233, 1.0, v233
	v_add_f32_e32 v234, 1.0, v234
	v_add_f32_e32 v235, 1.0, v235
	v_rcp_f32_e32 v232, v232
	v_rcp_f32_e32 v233, v233
	v_rcp_f32_e32 v234, v234
	v_rcp_f32_e32 v235, v235
	s_nop 0
	v_fma_f32 v232, v232, -2.0, 1.0
	v_fma_f32 v233, v233, -2.0, 1.0
	v_fma_f32 v234, v234, -2.0, 1.0
	v_fma_f32 v235, v235, -2.0, 1.0
	v_fma_f32 v20, v236, v232, v236
	v_fma_f32 v21, v237, v233, v237
	v_fma_f32 v22, v238, v234, v238
	v_fma_f32 v23, v239, v235, v239
	v_mul_f32_e32 v224, v24, v24
	v_mul_f32_e32 v225, v25, v25
	v_mul_f32_e32 v226, v26, v26
	v_mul_f32_e32 v227, v27, v27
	v_mul_f32_e32 v224, v224, v24
	v_mul_f32_e32 v225, v225, v25
	v_mul_f32_e32 v226, v226, v26
	v_mul_f32_e32 v227, v227, v27
	v_fma_f32 v228, s16, v224, v24
	v_fma_f32 v229, s16, v225, v25
	v_fma_f32 v230, s16, v226, v26
	v_fma_f32 v231, s16, v227, v27
	v_mul_f32_e32 v228, s18, v228
	v_mul_f32_e32 v229, s18, v229
	v_mul_f32_e32 v230, s18, v230
	v_mul_f32_e32 v231, s18, v231
	v_exp_f32_e32 v232, v228
	v_exp_f32_e32 v233, v229
	v_exp_f32_e32 v234, v230
	v_exp_f32_e32 v235, v231
	v_mul_f32_e32 v236, 0.5, v24
	v_mul_f32_e32 v237, 0.5, v25
	v_mul_f32_e32 v238, 0.5, v26
	v_mul_f32_e32 v239, 0.5, v27
	v_add_f32_e32 v232, 1.0, v232
	v_add_f32_e32 v233, 1.0, v233
	v_add_f32_e32 v234, 1.0, v234
	v_add_f32_e32 v235, 1.0, v235
	v_rcp_f32_e32 v232, v232
	v_rcp_f32_e32 v233, v233
	v_rcp_f32_e32 v234, v234
	v_rcp_f32_e32 v235, v235
	s_nop 0
	v_fma_f32 v232, v232, -2.0, 1.0
	v_fma_f32 v233, v233, -2.0, 1.0
	v_fma_f32 v234, v234, -2.0, 1.0
	v_fma_f32 v235, v235, -2.0, 1.0
	v_fma_f32 v24, v236, v232, v236
	v_fma_f32 v25, v237, v233, v237
	v_fma_f32 v26, v238, v234, v238
	v_fma_f32 v27, v239, v235, v239
	v_mul_f32_e32 v224, v28, v28
	v_mul_f32_e32 v225, v29, v29
	v_mul_f32_e32 v226, v30, v30
	v_mul_f32_e32 v227, v31, v31
	v_mul_f32_e32 v224, v224, v28
	v_mul_f32_e32 v225, v225, v29
	v_mul_f32_e32 v226, v226, v30
	v_mul_f32_e32 v227, v227, v31
	v_fma_f32 v228, s16, v224, v28
	v_fma_f32 v229, s16, v225, v29
	v_fma_f32 v230, s16, v226, v30
	v_fma_f32 v231, s16, v227, v31
	v_mul_f32_e32 v228, s18, v228
	v_mul_f32_e32 v229, s18, v229
	v_mul_f32_e32 v230, s18, v230
	v_mul_f32_e32 v231, s18, v231
	v_exp_f32_e32 v232, v228
	v_exp_f32_e32 v233, v229
	v_exp_f32_e32 v234, v230
	v_exp_f32_e32 v235, v231
	v_mul_f32_e32 v236, 0.5, v28
	v_mul_f32_e32 v237, 0.5, v29
	v_mul_f32_e32 v238, 0.5, v30
	v_mul_f32_e32 v239, 0.5, v31
	v_add_f32_e32 v232, 1.0, v232
	v_add_f32_e32 v233, 1.0, v233
	v_add_f32_e32 v234, 1.0, v234
	v_add_f32_e32 v235, 1.0, v235
	v_rcp_f32_e32 v232, v232
	v_rcp_f32_e32 v233, v233
	v_rcp_f32_e32 v234, v234
	v_rcp_f32_e32 v235, v235
	s_nop 0
	v_fma_f32 v232, v232, -2.0, 1.0
	v_fma_f32 v233, v233, -2.0, 1.0
	v_fma_f32 v234, v234, -2.0, 1.0
	v_fma_f32 v235, v235, -2.0, 1.0
	v_fma_f32 v28, v236, v232, v236
	v_fma_f32 v29, v237, v233, v237
	v_fma_f32 v30, v238, v234, v238
	v_fma_f32 v31, v239, v235, v239
; __global__ void __launch_bounds__(512, 2) hybrid_fwd(Params P) {
;     ...
; #pragma unroll
;                     for (int e = 0; e < 4; ++e) { const float t = hv[e], z = 0.7978845608028654f * (t + 0.044715f * t * t * t);
;                         const float th = 1.0f - 2.0f * __builtin_amdgcn_rcpf(1.0f + __expf(2.0f * z)); hv[e] = 0.5f * t * (1.0f + th); } }
	v_mul_f32_e32 v224, v32, v32
	v_mul_f32_e32 v225, v33, v33
	v_mul_f32_e32 v226, v34, v34
	v_mul_f32_e32 v227, v35, v35
	v_mul_f32_e32 v224, v224, v32
	v_mul_f32_e32 v225, v225, v33
	v_mul_f32_e32 v226, v226, v34
	v_mul_f32_e32 v227, v227, v35
	v_fma_f32 v228, s16, v224, v32
	v_fma_f32 v229, s16, v225, v33
	v_fma_f32 v230, s16, v226, v34
	v_fma_f32 v231, s16, v227, v35
	v_mul_f32_e32 v228, s18, v228
	v_mul_f32_e32 v229, s18, v229
	v_mul_f32_e32 v230, s18, v230
	v_mul_f32_e32 v231, s18, v231
	v_exp_f32_e32 v232, v228
	v_exp_f32_e32 v233, v229
	v_exp_f32_e32 v234, v230
	v_exp_f32_e32 v235, v231
	v_mul_f32_e32 v236, 0.5, v32
	v_mul_f32_e32 v237, 0.5, v33
	v_mul_f32_e32 v238, 0.5, v34
	v_mul_f32_e32 v239, 0.5, v35
	v_add_f32_e32 v232, 1.0, v232
	v_add_f32_e32 v233, 1.0, v233
	v_add_f32_e32 v234, 1.0, v234
	v_add_f32_e32 v235, 1.0, v235
	v_rcp_f32_e32 v232, v232
	v_rcp_f32_e32 v233, v233
	v_rcp_f32_e32 v234, v234
	v_rcp_f32_e32 v235, v235
	s_nop 0
	v_fma_f32 v232, v232, -2.0, 1.0
	v_fma_f32 v233, v233, -2.0, 1.0
	v_fma_f32 v234, v234, -2.0, 1.0
	v_fma_f32 v235, v235, -2.0, 1.0
	v_fma_f32 v32, v236, v232, v236
	v_fma_f32 v33, v237, v233, v237
	v_fma_f32 v34, v238, v234, v238
	v_fma_f32 v35, v239, v235, v239
	v_mul_f32_e32 v224, v36, v36
	v_mul_f32_e32 v225, v37, v37
	v_mul_f32_e32 v226, v38, v38
	v_mul_f32_e32 v227, v39, v39
	v_mul_f32_e32 v224, v224, v36
	v_mul_f32_e32 v225, v225, v37
	v_mul_f32_e32 v226, v226, v38
	v_mul_f32_e32 v227, v227, v39
	v_fma_f32 v228, s16, v224, v36
	v_fma_f32 v229, s16, v225, v37
	v_fma_f32 v230, s16, v226, v38
	v_fma_f32 v231, s16, v227, v39
	v_mul_f32_e32 v228, s18, v228
	v_mul_f32_e32 v229, s18, v229
	v_mul_f32_e32 v230, s18, v230
	v_mul_f32_e32 v231, s18, v231
	v_exp_f32_e32 v232, v228
	v_exp_f32_e32 v233, v229
	v_exp_f32_e32 v234, v230
	v_exp_f32_e32 v235, v231
	v_mul_f32_e32 v236, 0.5, v36
	v_mul_f32_e32 v237, 0.5, v37
	v_mul_f32_e32 v238, 0.5, v38
	v_mul_f32_e32 v239, 0.5, v39
	v_add_f32_e32 v232, 1.0, v232
	v_add_f32_e32 v233, 1.0, v233
	v_add_f32_e32 v234, 1.0, v234
	v_add_f32_e32 v235, 1.0, v235
	v_rcp_f32_e32 v232, v232
	v_rcp_f32_e32 v233, v233
	v_rcp_f32_e32 v234, v234
	v_rcp_f32_e32 v235, v235
	s_nop 0
	v_fma_f32 v232, v232, -2.0, 1.0
	v_fma_f32 v233, v233, -2.0, 1.0
	v_fma_f32 v234, v234, -2.0, 1.0
	v_fma_f32 v235, v235, -2.0, 1.0
	v_fma_f32 v36, v236, v232, v236
	v_fma_f32 v37, v237, v233, v237
	v_fma_f32 v38, v238, v234, v238
	v_fma_f32 v39, v239, v235, v239
	v_mul_f32_e32 v224, v40, v40
	v_mul_f32_e32 v225, v41, v41
	v_mul_f32_e32 v226, v42, v42
	v_mul_f32_e32 v227, v43, v43
	v_mul_f32_e32 v224, v224, v40
	v_mul_f32_e32 v225, v225, v41
	v_mul_f32_e32 v226, v226, v42
	v_mul_f32_e32 v227, v227, v43
	v_fma_f32 v228, s16, v224, v40
	v_fma_f32 v229, s16, v225, v41
	v_fma_f32 v230, s16, v226, v42
	v_fma_f32 v231, s16, v227, v43
	v_mul_f32_e32 v228, s18, v228
	v_mul_f32_e32 v229, s18, v229
	v_mul_f32_e32 v230, s18, v230
	v_mul_f32_e32 v231, s18, v231
	v_exp_f32_e32 v232, v228
	v_exp_f32_e32 v233, v229
	v_exp_f32_e32 v234, v230
	v_exp_f32_e32 v235, v231
	v_mul_f32_e32 v236, 0.5, v40
	v_mul_f32_e32 v237, 0.5, v41
	v_mul_f32_e32 v238, 0.5, v42
	v_mul_f32_e32 v239, 0.5, v43
	v_add_f32_e32 v232, 1.0, v232
	v_add_f32_e32 v233, 1.0, v233
	v_add_f32_e32 v234, 1.0, v234
	v_add_f32_e32 v235, 1.0, v235
	v_rcp_f32_e32 v232, v232
	v_rcp_f32_e32 v233, v233
	v_rcp_f32_e32 v234, v234
	v_rcp_f32_e32 v235, v235
	s_nop 0
	v_fma_f32 v232, v232, -2.0, 1.0
	v_fma_f32 v233, v233, -2.0, 1.0
	v_fma_f32 v234, v234, -2.0, 1.0
	v_fma_f32 v235, v235, -2.0, 1.0
	v_fma_f32 v40, v236, v232, v236
	v_fma_f32 v41, v237, v233, v237
	v_fma_f32 v42, v238, v234, v238
	v_fma_f32 v43, v239, v235, v239
	v_mul_f32_e32 v224, v44, v44
	v_mul_f32_e32 v225, v45, v45
	v_mul_f32_e32 v226, v46, v46
	v_mul_f32_e32 v227, v47, v47
	v_mul_f32_e32 v224, v224, v44
	v_mul_f32_e32 v225, v225, v45
	v_mul_f32_e32 v226, v226, v46
	v_mul_f32_e32 v227, v227, v47
	v_fma_f32 v228, s16, v224, v44
	v_fma_f32 v229, s16, v225, v45
	v_fma_f32 v230, s16, v226, v46
	v_fma_f32 v231, s16, v227, v47
	v_mul_f32_e32 v228, s18, v228
	v_mul_f32_e32 v229, s18, v229
	v_mul_f32_e32 v230, s18, v230
	v_mul_f32_e32 v231, s18, v231
	v_exp_f32_e32 v232, v228
	v_exp_f32_e32 v233, v229
	v_exp_f32_e32 v234, v230
	v_exp_f32_e32 v235, v231
	v_mul_f32_e32 v236, 0.5, v44
	v_mul_f32_e32 v237, 0.5, v45
	v_mul_f32_e32 v238, 0.5, v46
	v_mul_f32_e32 v239, 0.5, v47
	v_add_f32_e32 v232, 1.0, v232
	v_add_f32_e32 v233, 1.0, v233
	v_add_f32_e32 v234, 1.0, v234
	v_add_f32_e32 v235, 1.0, v235
	v_rcp_f32_e32 v232, v232
	v_rcp_f32_e32 v233, v233
	v_rcp_f32_e32 v234, v234
	v_rcp_f32_e32 v235, v235
	s_nop 0
	v_fma_f32 v232, v232, -2.0, 1.0
	v_fma_f32 v233, v233, -2.0, 1.0
	v_fma_f32 v234, v234, -2.0, 1.0
	v_fma_f32 v235, v235, -2.0, 1.0
	v_fma_f32 v44, v236, v232, v236
	v_fma_f32 v45, v237, v233, v237
	v_fma_f32 v46, v238, v234, v238
	v_fma_f32 v47, v239, v235, v239
	v_mul_f32_e32 v224, v48, v48
	v_mul_f32_e32 v225, v49, v49
	v_mul_f32_e32 v226, v50, v50
	v_mul_f32_e32 v227, v51, v51
	v_mul_f32_e32 v224, v224, v48
	v_mul_f32_e32 v225, v225, v49
	v_mul_f32_e32 v226, v226, v50
	v_mul_f32_e32 v227, v227, v51
	v_fma_f32 v228, s16, v224, v48
	v_fma_f32 v229, s16, v225, v49
	v_fma_f32 v230, s16, v226, v50
	v_fma_f32 v231, s16, v227, v51
	v_mul_f32_e32 v228, s18, v228
	v_mul_f32_e32 v229, s18, v229
	v_mul_f32_e32 v230, s18, v230
	v_mul_f32_e32 v231, s18, v231
	v_exp_f32_e32 v232, v228
	v_exp_f32_e32 v233, v229
	v_exp_f32_e32 v234, v230
	v_exp_f32_e32 v235, v231
	v_mul_f32_e32 v236, 0.5, v48
	v_mul_f32_e32 v237, 0.5, v49
	v_mul_f32_e32 v238, 0.5, v50
	v_mul_f32_e32 v239, 0.5, v51
	v_add_f32_e32 v232, 1.0, v232
; __global__ void __launch_bounds__(512, 2) hybrid_fwd(Params P) {
;     ...
; #pragma unroll
;                     for (int e = 0; e < 4; ++e) { const float t = hv[e], z = 0.7978845608028654f * (t + 0.044715f * t * t * t);
;                         const float th = 1.0f - 2.0f * __builtin_amdgcn_rcpf(1.0f + __expf(2.0f * z)); hv[e] = 0.5f * t * (1.0f + th); } }
;                 const float* wp = cw2 + (size_t)kv * 256 * 64 + lane; float a = 0.f;
; #pragma unroll
;                 for (int k = 0; k < 256; ++k) { const float hk = __uint_as_float(__builtin_amdgcn_readlane(__float_as_uint(hv[k & 3]), k >> 2)); a = fmaf(hk, wp[k * 64], a); }
	v_add_f32_e32 v233, 1.0, v233
	v_add_f32_e32 v234, 1.0, v234
	v_add_f32_e32 v235, 1.0, v235
	v_rcp_f32_e32 v232, v232
	v_rcp_f32_e32 v233, v233
	v_rcp_f32_e32 v234, v234
	v_rcp_f32_e32 v235, v235
	s_nop 0
	v_fma_f32 v232, v232, -2.0, 1.0
	v_fma_f32 v233, v233, -2.0, 1.0
	v_fma_f32 v234, v234, -2.0, 1.0
	v_fma_f32 v235, v235, -2.0, 1.0
	v_fma_f32 v48, v236, v232, v236
	v_fma_f32 v49, v237, v233, v237
	v_fma_f32 v50, v238, v234, v238
	v_fma_f32 v51, v239, v235, v239
	v_mul_f32_e32 v224, v52, v52
	v_mul_f32_e32 v225, v53, v53
	v_mul_f32_e32 v226, v54, v54
	v_mul_f32_e32 v227, v55, v55
	v_mul_f32_e32 v224, v224, v52
	v_mul_f32_e32 v225, v225, v53
	v_mul_f32_e32 v226, v226, v54
	v_mul_f32_e32 v227, v227, v55
	v_fma_f32 v228, s16, v224, v52
	v_fma_f32 v229, s16, v225, v53
	v_fma_f32 v230, s16, v226, v54
	v_fma_f32 v231, s16, v227, v55
	v_mul_f32_e32 v228, s18, v228
	v_mul_f32_e32 v229, s18, v229
	v_mul_f32_e32 v230, s18, v230
	v_mul_f32_e32 v231, s18, v231
	v_exp_f32_e32 v232, v228
	v_exp_f32_e32 v233, v229
	v_exp_f32_e32 v234, v230
	v_exp_f32_e32 v235, v231
	v_mul_f32_e32 v236, 0.5, v52
	v_mul_f32_e32 v237, 0.5, v53
	v_mul_f32_e32 v238, 0.5, v54
	v_mul_f32_e32 v239, 0.5, v55
	v_add_f32_e32 v232, 1.0, v232
	v_add_f32_e32 v233, 1.0, v233
	v_add_f32_e32 v234, 1.0, v234
	v_add_f32_e32 v235, 1.0, v235
	v_rcp_f32_e32 v232, v232
	v_rcp_f32_e32 v233, v233
	v_rcp_f32_e32 v234, v234
	v_rcp_f32_e32 v235, v235
	s_nop 0
	v_fma_f32 v232, v232, -2.0, 1.0
	v_fma_f32 v233, v233, -2.0, 1.0
	v_fma_f32 v234, v234, -2.0, 1.0
	v_fma_f32 v235, v235, -2.0, 1.0
	v_fma_f32 v52, v236, v232, v236
	v_fma_f32 v53, v237, v233, v237
	v_fma_f32 v54, v238, v234, v238
	v_fma_f32 v55, v239, v235, v239
	v_mul_f32_e32 v224, v56, v56
	v_mul_f32_e32 v225, v57, v57
	v_mul_f32_e32 v226, v58, v58
	v_mul_f32_e32 v227, v59, v59
	v_mul_f32_e32 v224, v224, v56
	v_mul_f32_e32 v225, v225, v57
	v_mul_f32_e32 v226, v226, v58
	v_mul_f32_e32 v227, v227, v59
	v_fma_f32 v228, s16, v224, v56
	v_fma_f32 v229, s16, v225, v57
	v_fma_f32 v230, s16, v226, v58
	v_fma_f32 v231, s16, v227, v59
	v_mul_f32_e32 v228, s18, v228
	v_mul_f32_e32 v229, s18, v229
	v_mul_f32_e32 v230, s18, v230
	v_mul_f32_e32 v231, s18, v231
	v_exp_f32_e32 v232, v228
	v_exp_f32_e32 v233, v229
	v_exp_f32_e32 v234, v230
	v_exp_f32_e32 v235, v231
	v_mul_f32_e32 v236, 0.5, v56
	v_mul_f32_e32 v237, 0.5, v57
	v_mul_f32_e32 v238, 0.5, v58
	v_mul_f32_e32 v239, 0.5, v59
	v_add_f32_e32 v232, 1.0, v232
	v_add_f32_e32 v233, 1.0, v233
	v_add_f32_e32 v234, 1.0, v234
	v_add_f32_e32 v235, 1.0, v235
	v_rcp_f32_e32 v232, v232
	v_rcp_f32_e32 v233, v233
	v_rcp_f32_e32 v234, v234
	v_rcp_f32_e32 v235, v235
	s_nop 0
	v_fma_f32 v232, v232, -2.0, 1.0
	v_fma_f32 v233, v233, -2.0, 1.0
	v_fma_f32 v234, v234, -2.0, 1.0
	v_fma_f32 v235, v235, -2.0, 1.0
	v_fma_f32 v56, v236, v232, v236
	v_fma_f32 v57, v237, v233, v237
	v_fma_f32 v58, v238, v234, v238
	v_fma_f32 v59, v239, v235, v239
	v_mul_f32_e32 v224, v60, v60
	v_mul_f32_e32 v225, v61, v61
	v_mul_f32_e32 v226, v62, v62
	v_mul_f32_e32 v227, v63, v63
	v_mul_f32_e32 v224, v224, v60
	v_mul_f32_e32 v225, v225, v61
	v_mul_f32_e32 v226, v226, v62
	v_mul_f32_e32 v227, v227, v63
	v_fma_f32 v228, s16, v224, v60
	v_fma_f32 v229, s16, v225, v61
	v_fma_f32 v230, s16, v226, v62
	v_fma_f32 v231, s16, v227, v63
	v_mul_f32_e32 v228, s18, v228
	v_mul_f32_e32 v229, s18, v229
	v_mul_f32_e32 v230, s18, v230
	v_mul_f32_e32 v231, s18, v231
	v_exp_f32_e32 v232, v228
	v_exp_f32_e32 v233, v229
	v_exp_f32_e32 v234, v230
	v_exp_f32_e32 v235, v231
	v_mul_f32_e32 v236, 0.5, v60
	v_mul_f32_e32 v237, 0.5, v61
	v_mul_f32_e32 v238, 0.5, v62
	v_mul_f32_e32 v239, 0.5, v63
	v_add_f32_e32 v232, 1.0, v232
	v_add_f32_e32 v233, 1.0, v233
	v_add_f32_e32 v234, 1.0, v234
	v_add_f32_e32 v235, 1.0, v235
	v_rcp_f32_e32 v232, v232
	v_rcp_f32_e32 v233, v233
	v_rcp_f32_e32 v234, v234
	v_rcp_f32_e32 v235, v235
	s_nop 0
	v_fma_f32 v232, v232, -2.0, 1.0
	v_fma_f32 v233, v233, -2.0, 1.0
	v_fma_f32 v234, v234, -2.0, 1.0
	v_fma_f32 v235, v235, -2.0, 1.0
	v_fma_f32 v60, v236, v232, v236
	v_fma_f32 v61, v237, v233, v237
	v_fma_f32 v62, v238, v234, v238
	v_fma_f32 v63, v239, v235, v239
	v_mov_b32_e32 v64, 0
	v_mov_b32_e32 v65, 0
	v_mov_b32_e32 v66, 0
	v_mov_b32_e32 v67, 0
	v_mov_b32_e32 v68, 0
	v_mov_b32_e32 v69, 0
	v_mov_b32_e32 v70, 0
	v_mov_b32_e32 v71, 0
	v_mov_b32_e32 v72, 0
	v_mov_b32_e32 v73, 0
	v_mov_b32_e32 v74, 0
	v_mov_b32_e32 v75, 0
	v_mov_b32_e32 v76, 0
	v_mov_b32_e32 v77, 0
	v_mov_b32_e32 v78, 0
	v_mov_b32_e32 v79, 0
	global_load_dwordx4 v[152:155], v249, s[10:11]
	global_load_dwordx4 v[156:159], v249, s[10:11] offset:256
	global_load_dwordx4 v[160:163], v249, s[10:11] offset:512
	global_load_dwordx4 v[170:173], v249, s[10:11] offset:768
	global_load_dwordx4 v[174:177], v249, s[10:11] offset:1024
	global_load_dwordx4 v[178:181], v249, s[10:11] offset:1280
	global_load_dwordx4 v[182:185], v249, s[10:11] offset:1536
	global_load_dwordx4 v[220:223], v249, s[10:11] offset:1792
	s_add_u32 s10, s10, 0x800
	s_addc_u32 s11, s11, 0
	s_waitcnt vmcnt(16)
; __global__ void __launch_bounds__(512, 2) hybrid_fwd(Params P) {
;     ...
;                 const float* wp = cw2 + (size_t)kv * 256 * 64 + lane; float a = 0.f;
; #pragma unroll
;                 for (int k = 0; k < 256; ++k) { const float hk = __uint_as_float(__builtin_amdgcn_readlane(__float_as_uint(hv[k & 3]), k >> 2)); a = fmaf(hk, wp[k * 64], a); }
	v_mfma_f32_16x16x4_f32 v[64:67], v0, v82, v[64:67]
	v_mfma_f32_16x16x4_f32 v[68:71], v0, v83, v[68:71]
	v_mfma_f32_16x16x4_f32 v[72:75], v0, v84, v[72:75]
	v_mfma_f32_16x16x4_f32 v[76:79], v0, v85, v[76:79]
	v_mfma_f32_16x16x4_f32 v[64:67], v1, v86, v[64:67]
	v_mfma_f32_16x16x4_f32 v[68:71], v1, v87, v[68:71]
	v_mfma_f32_16x16x4_f32 v[72:75], v1, v88, v[72:75]
	v_mfma_f32_16x16x4_f32 v[76:79], v1, v89, v[76:79]
	v_mfma_f32_16x16x4_f32 v[64:67], v2, v90, v[64:67]
	v_mfma_f32_16x16x4_f32 v[68:71], v2, v91, v[68:71]
	v_mfma_f32_16x16x4_f32 v[72:75], v2, v92, v[72:75]
	v_mfma_f32_16x16x4_f32 v[76:79], v2, v93, v[76:79]
	v_mfma_f32_16x16x4_f32 v[64:67], v3, v94, v[64:67]
	v_mfma_f32_16x16x4_f32 v[68:71], v3, v95, v[68:71]
	v_mfma_f32_16x16x4_f32 v[72:75], v3, v96, v[72:75]
	v_mfma_f32_16x16x4_f32 v[76:79], v3, v97, v[76:79]
	v_mfma_f32_16x16x4_f32 v[64:67], v4, v98, v[64:67]
	v_mfma_f32_16x16x4_f32 v[68:71], v4, v99, v[68:71]
	v_mfma_f32_16x16x4_f32 v[72:75], v4, v100, v[72:75]
	v_mfma_f32_16x16x4_f32 v[76:79], v4, v101, v[76:79]
	v_mfma_f32_16x16x4_f32 v[64:67], v5, v102, v[64:67]
	v_mfma_f32_16x16x4_f32 v[68:71], v5, v103, v[68:71]
	v_mfma_f32_16x16x4_f32 v[72:75], v5, v104, v[72:75]
	v_mfma_f32_16x16x4_f32 v[76:79], v5, v105, v[76:79]
	v_mfma_f32_16x16x4_f32 v[64:67], v6, v106, v[64:67]
	v_mfma_f32_16x16x4_f32 v[68:71], v6, v107, v[68:71]
	v_mfma_f32_16x16x4_f32 v[72:75], v6, v108, v[72:75]
	v_mfma_f32_16x16x4_f32 v[76:79], v6, v109, v[76:79]
	v_mfma_f32_16x16x4_f32 v[64:67], v7, v110, v[64:67]
	v_mfma_f32_16x16x4_f32 v[68:71], v7, v111, v[68:71]
	v_mfma_f32_16x16x4_f32 v[72:75], v7, v112, v[72:75]
	v_mfma_f32_16x16x4_f32 v[76:79], v7, v113, v[76:79]
	global_load_dwordx4 v[82:85], v249, s[10:11]
	global_load_dwordx4 v[86:89], v249, s[10:11] offset:256
	global_load_dwordx4 v[90:93], v249, s[10:11] offset:512
	global_load_dwordx4 v[94:97], v249, s[10:11] offset:768
	global_load_dwordx4 v[98:101], v249, s[10:11] offset:1024
	global_load_dwordx4 v[102:105], v249, s[10:11] offset:1280
	global_load_dwordx4 v[106:109], v249, s[10:11] offset:1536
	global_load_dwordx4 v[110:113], v249, s[10:11] offset:1792
	s_add_u32 s10, s10, 0x800
	s_addc_u32 s11, s11, 0
	s_waitcnt vmcnt(16)
	v_mfma_f32_16x16x4_f32 v[64:67], v8, v114, v[64:67]
	v_mfma_f32_16x16x4_f32 v[68:71], v8, v115, v[68:71]
	v_mfma_f32_16x16x4_f32 v[72:75], v8, v116, v[72:75]
	v_mfma_f32_16x16x4_f32 v[76:79], v8, v117, v[76:79]
	v_mfma_f32_16x16x4_f32 v[64:67], v9, v118, v[64:67]
	v_mfma_f32_16x16x4_f32 v[68:71], v9, v119, v[68:71]
	v_mfma_f32_16x16x4_f32 v[72:75], v9, v120, v[72:75]
	v_mfma_f32_16x16x4_f32 v[76:79], v9, v121, v[76:79]
	v_mfma_f32_16x16x4_f32 v[64:67], v10, v122, v[64:67]
	v_mfma_f32_16x16x4_f32 v[68:71], v10, v123, v[68:71]
	v_mfma_f32_16x16x4_f32 v[72:75], v10, v124, v[72:75]
	v_mfma_f32_16x16x4_f32 v[76:79], v10, v125, v[76:79]
	v_mfma_f32_16x16x4_f32 v[64:67], v11, v126, v[64:67]
	v_mfma_f32_16x16x4_f32 v[68:71], v11, v127, v[68:71]
	v_mfma_f32_16x16x4_f32 v[72:75], v11, v128, v[72:75]
	v_mfma_f32_16x16x4_f32 v[76:79], v11, v129, v[76:79]
	v_mfma_f32_16x16x4_f32 v[64:67], v12, v130, v[64:67]
	v_mfma_f32_16x16x4_f32 v[68:71], v12, v131, v[68:71]
	v_mfma_f32_16x16x4_f32 v[72:75], v12, v132, v[72:75]
	v_mfma_f32_16x16x4_f32 v[76:79], v12, v133, v[76:79]
	v_mfma_f32_16x16x4_f32 v[64:67], v13, v134, v[64:67]
	v_mfma_f32_16x16x4_f32 v[68:71], v13, v135, v[68:71]
	v_mfma_f32_16x16x4_f32 v[72:75], v13, v136, v[72:75]
	v_mfma_f32_16x16x4_f32 v[76:79], v13, v137, v[76:79]
	v_mfma_f32_16x16x4_f32 v[64:67], v14, v138, v[64:67]
	v_mfma_f32_16x16x4_f32 v[68:71], v14, v139, v[68:71]
	v_mfma_f32_16x16x4_f32 v[72:75], v14, v140, v[72:75]
	v_mfma_f32_16x16x4_f32 v[76:79], v14, v141, v[76:79]
	v_mfma_f32_16x16x4_f32 v[64:67], v15, v142, v[64:67]
	v_mfma_f32_16x16x4_f32 v[68:71], v15, v143, v[68:71]
	v_mfma_f32_16x16x4_f32 v[72:75], v15, v144, v[72:75]
	v_mfma_f32_16x16x4_f32 v[76:79], v15, v145, v[76:79]
	global_load_dwordx4 v[114:117], v249, s[10:11]
	global_load_dwordx4 v[118:121], v249, s[10:11] offset:256
	global_load_dwordx4 v[122:125], v249, s[10:11] offset:512
	global_load_dwordx4 v[126:129], v249, s[10:11] offset:768
	global_load_dwordx4 v[130:133], v249, s[10:11] offset:1024
	global_load_dwordx4 v[134:137], v249, s[10:11] offset:1280
	global_load_dwordx4 v[138:141], v249, s[10:11] offset:1536
	global_load_dwordx4 v[142:145], v249, s[10:11] offset:1792
	s_add_u32 s10, s10, 0x800
	s_addc_u32 s11, s11, 0
	s_waitcnt vmcnt(16)
	v_mfma_f32_16x16x4_f32 v[64:67], v16, v152, v[64:67]
	v_mfma_f32_16x16x4_f32 v[68:71], v16, v153, v[68:71]
	v_mfma_f32_16x16x4_f32 v[72:75], v16, v154, v[72:75]
	v_mfma_f32_16x16x4_f32 v[76:79], v16, v155, v[76:79]
	v_mfma_f32_16x16x4_f32 v[64:67], v17, v156, v[64:67]
	v_mfma_f32_16x16x4_f32 v[68:71], v17, v157, v[68:71]
	v_mfma_f32_16x16x4_f32 v[72:75], v17, v158, v[72:75]
	v_mfma_f32_16x16x4_f32 v[76:79], v17, v159, v[76:79]
	v_mfma_f32_16x16x4_f32 v[64:67], v18, v160, v[64:67]
	v_mfma_f32_16x16x4_f32 v[68:71], v18, v161, v[68:71]
	v_mfma_f32_16x16x4_f32 v[72:75], v18, v162, v[72:75]
	v_mfma_f32_16x16x4_f32 v[76:79], v18, v163, v[76:79]
	v_mfma_f32_16x16x4_f32 v[64:67], v19, v170, v[64:67]
	v_mfma_f32_16x16x4_f32 v[68:71], v19, v171, v[68:71]
	v_mfma_f32_16x16x4_f32 v[72:75], v19, v172, v[72:75]
	v_mfma_f32_16x16x4_f32 v[76:79], v19, v173, v[76:79]
	v_mfma_f32_16x16x4_f32 v[64:67], v20, v174, v[64:67]
	v_mfma_f32_16x16x4_f32 v[68:71], v20, v175, v[68:71]
	v_mfma_f32_16x16x4_f32 v[72:75], v20, v176, v[72:75]
	v_mfma_f32_16x16x4_f32 v[76:79], v20, v177, v[76:79]
	v_mfma_f32_16x16x4_f32 v[64:67], v21, v178, v[64:67]
	v_mfma_f32_16x16x4_f32 v[68:71], v21, v179, v[68:71]
	v_mfma_f32_16x16x4_f32 v[72:75], v21, v180, v[72:75]
	v_mfma_f32_16x16x4_f32 v[76:79], v21, v181, v[76:79]
	v_mfma_f32_16x16x4_f32 v[64:67], v22, v182, v[64:67]
	v_mfma_f32_16x16x4_f32 v[68:71], v22, v183, v[68:71]
	v_mfma_f32_16x16x4_f32 v[72:75], v22, v184, v[72:75]
	v_mfma_f32_16x16x4_f32 v[76:79], v22, v185, v[76:79]
	v_mfma_f32_16x16x4_f32 v[64:67], v23, v220, v[64:67]
	v_mfma_f32_16x16x4_f32 v[68:71], v23, v221, v[68:71]
	v_mfma_f32_16x16x4_f32 v[72:75], v23, v222, v[72:75]
	v_mfma_f32_16x16x4_f32 v[76:79], v23, v223, v[76:79]
	global_load_dwordx4 v[152:155], v249, s[10:11]
	global_load_dwordx4 v[156:159], v249, s[10:11] offset:256
	global_load_dwordx4 v[160:163], v249, s[10:11] offset:512
	global_load_dwordx4 v[170:173], v249, s[10:11] offset:768
	global_load_dwordx4 v[174:177], v249, s[10:11] offset:1024
	global_load_dwordx4 v[178:181], v249, s[10:11] offset:1280
	global_load_dwordx4 v[182:185], v249, s[10:11] offset:1536
	global_load_dwordx4 v[220:223], v249, s[10:11] offset:1792
	s_add_u32 s10, s10, 0x800
	s_addc_u32 s11, s11, 0
	s_waitcnt vmcnt(16)
; __global__ void __launch_bounds__(512, 2) hybrid_fwd(Params P) {
;     ...
;                 const float* wp = cw2 + (size_t)kv * 256 * 64 + lane; float a = 0.f;
; #pragma unroll
;                 for (int k = 0; k < 256; ++k) { const float hk = __uint_as_float(__builtin_amdgcn_readlane(__float_as_uint(hv[k & 3]), k >> 2)); a = fmaf(hk, wp[k * 64], a); }
	v_mfma_f32_16x16x4_f32 v[64:67], v24, v82, v[64:67]
	v_mfma_f32_16x16x4_f32 v[68:71], v24, v83, v[68:71]
	v_mfma_f32_16x16x4_f32 v[72:75], v24, v84, v[72:75]
	v_mfma_f32_16x16x4_f32 v[76:79], v24, v85, v[76:79]
	v_mfma_f32_16x16x4_f32 v[64:67], v25, v86, v[64:67]
	v_mfma_f32_16x16x4_f32 v[68:71], v25, v87, v[68:71]
	v_mfma_f32_16x16x4_f32 v[72:75], v25, v88, v[72:75]
	v_mfma_f32_16x16x4_f32 v[76:79], v25, v89, v[76:79]
	v_mfma_f32_16x16x4_f32 v[64:67], v26, v90, v[64:67]
	v_mfma_f32_16x16x4_f32 v[68:71], v26, v91, v[68:71]
	v_mfma_f32_16x16x4_f32 v[72:75], v26, v92, v[72:75]
	v_mfma_f32_16x16x4_f32 v[76:79], v26, v93, v[76:79]
	v_mfma_f32_16x16x4_f32 v[64:67], v27, v94, v[64:67]
	v_mfma_f32_16x16x4_f32 v[68:71], v27, v95, v[68:71]
	v_mfma_f32_16x16x4_f32 v[72:75], v27, v96, v[72:75]
	v_mfma_f32_16x16x4_f32 v[76:79], v27, v97, v[76:79]
	v_mfma_f32_16x16x4_f32 v[64:67], v28, v98, v[64:67]
	v_mfma_f32_16x16x4_f32 v[68:71], v28, v99, v[68:71]
	v_mfma_f32_16x16x4_f32 v[72:75], v28, v100, v[72:75]
	v_mfma_f32_16x16x4_f32 v[76:79], v28, v101, v[76:79]
	v_mfma_f32_16x16x4_f32 v[64:67], v29, v102, v[64:67]
	v_mfma_f32_16x16x4_f32 v[68:71], v29, v103, v[68:71]
	v_mfma_f32_16x16x4_f32 v[72:75], v29, v104, v[72:75]
	v_mfma_f32_16x16x4_f32 v[76:79], v29, v105, v[76:79]
	v_mfma_f32_16x16x4_f32 v[64:67], v30, v106, v[64:67]
	v_mfma_f32_16x16x4_f32 v[68:71], v30, v107, v[68:71]
	v_mfma_f32_16x16x4_f32 v[72:75], v30, v108, v[72:75]
	v_mfma_f32_16x16x4_f32 v[76:79], v30, v109, v[76:79]
	v_mfma_f32_16x16x4_f32 v[64:67], v31, v110, v[64:67]
	v_mfma_f32_16x16x4_f32 v[68:71], v31, v111, v[68:71]
	v_mfma_f32_16x16x4_f32 v[72:75], v31, v112, v[72:75]
	v_mfma_f32_16x16x4_f32 v[76:79], v31, v113, v[76:79]
	global_load_dwordx4 v[82:85], v249, s[10:11]
	global_load_dwordx4 v[86:89], v249, s[10:11] offset:256
	global_load_dwordx4 v[90:93], v249, s[10:11] offset:512
	global_load_dwordx4 v[94:97], v249, s[10:11] offset:768
	global_load_dwordx4 v[98:101], v249, s[10:11] offset:1024
	global_load_dwordx4 v[102:105], v249, s[10:11] offset:1280
	global_load_dwordx4 v[106:109], v249, s[10:11] offset:1536
	global_load_dwordx4 v[110:113], v249, s[10:11] offset:1792
	s_add_u32 s10, s10, 0x800
	s_addc_u32 s11, s11, 0
	s_waitcnt vmcnt(16)
	v_mfma_f32_16x16x4_f32 v[64:67], v32, v114, v[64:67]
	v_mfma_f32_16x16x4_f32 v[68:71], v32, v115, v[68:71]
	v_mfma_f32_16x16x4_f32 v[72:75], v32, v116, v[72:75]
	v_mfma_f32_16x16x4_f32 v[76:79], v32, v117, v[76:79]
	v_mfma_f32_16x16x4_f32 v[64:67], v33, v118, v[64:67]
	v_mfma_f32_16x16x4_f32 v[68:71], v33, v119, v[68:71]
	v_mfma_f32_16x16x4_f32 v[72:75], v33, v120, v[72:75]
	v_mfma_f32_16x16x4_f32 v[76:79], v33, v121, v[76:79]
	v_mfma_f32_16x16x4_f32 v[64:67], v34, v122, v[64:67]
	v_mfma_f32_16x16x4_f32 v[68:71], v34, v123, v[68:71]
	v_mfma_f32_16x16x4_f32 v[72:75], v34, v124, v[72:75]
	v_mfma_f32_16x16x4_f32 v[76:79], v34, v125, v[76:79]
	v_mfma_f32_16x16x4_f32 v[64:67], v35, v126, v[64:67]
	v_mfma_f32_16x16x4_f32 v[68:71], v35, v127, v[68:71]
	v_mfma_f32_16x16x4_f32 v[72:75], v35, v128, v[72:75]
	v_mfma_f32_16x16x4_f32 v[76:79], v35, v129, v[76:79]
	v_mfma_f32_16x16x4_f32 v[64:67], v36, v130, v[64:67]
	v_mfma_f32_16x16x4_f32 v[68:71], v36, v131, v[68:71]
	v_mfma_f32_16x16x4_f32 v[72:75], v36, v132, v[72:75]
	v_mfma_f32_16x16x4_f32 v[76:79], v36, v133, v[76:79]
	v_mfma_f32_16x16x4_f32 v[64:67], v37, v134, v[64:67]
	v_mfma_f32_16x16x4_f32 v[68:71], v37, v135, v[68:71]
	v_mfma_f32_16x16x4_f32 v[72:75], v37, v136, v[72:75]
	v_mfma_f32_16x16x4_f32 v[76:79], v37, v137, v[76:79]
	v_mfma_f32_16x16x4_f32 v[64:67], v38, v138, v[64:67]
	v_mfma_f32_16x16x4_f32 v[68:71], v38, v139, v[68:71]
	v_mfma_f32_16x16x4_f32 v[72:75], v38, v140, v[72:75]
	v_mfma_f32_16x16x4_f32 v[76:79], v38, v141, v[76:79]
	v_mfma_f32_16x16x4_f32 v[64:67], v39, v142, v[64:67]
	v_mfma_f32_16x16x4_f32 v[68:71], v39, v143, v[68:71]
	v_mfma_f32_16x16x4_f32 v[72:75], v39, v144, v[72:75]
	v_mfma_f32_16x16x4_f32 v[76:79], v39, v145, v[76:79]
	global_load_dwordx4 v[114:117], v249, s[10:11]
	global_load_dwordx4 v[118:121], v249, s[10:11] offset:256
	global_load_dwordx4 v[122:125], v249, s[10:11] offset:512
	global_load_dwordx4 v[126:129], v249, s[10:11] offset:768
	global_load_dwordx4 v[130:133], v249, s[10:11] offset:1024
	global_load_dwordx4 v[134:137], v249, s[10:11] offset:1280
	global_load_dwordx4 v[138:141], v249, s[10:11] offset:1536
	global_load_dwordx4 v[142:145], v249, s[10:11] offset:1792
	s_add_u32 s10, s10, 0x800
	s_addc_u32 s11, s11, 0
	s_waitcnt vmcnt(16)
	v_mfma_f32_16x16x4_f32 v[64:67], v40, v152, v[64:67]
	v_mfma_f32_16x16x4_f32 v[68:71], v40, v153, v[68:71]
	v_mfma_f32_16x16x4_f32 v[72:75], v40, v154, v[72:75]
	v_mfma_f32_16x16x4_f32 v[76:79], v40, v155, v[76:79]
	v_mfma_f32_16x16x4_f32 v[64:67], v41, v156, v[64:67]
	v_mfma_f32_16x16x4_f32 v[68:71], v41, v157, v[68:71]
	v_mfma_f32_16x16x4_f32 v[72:75], v41, v158, v[72:75]
	v_mfma_f32_16x16x4_f32 v[76:79], v41, v159, v[76:79]
	v_mfma_f32_16x16x4_f32 v[64:67], v42, v160, v[64:67]
	v_mfma_f32_16x16x4_f32 v[68:71], v42, v161, v[68:71]
	v_mfma_f32_16x16x4_f32 v[72:75], v42, v162, v[72:75]
	v_mfma_f32_16x16x4_f32 v[76:79], v42, v163, v[76:79]
	v_mfma_f32_16x16x4_f32 v[64:67], v43, v170, v[64:67]
	v_mfma_f32_16x16x4_f32 v[68:71], v43, v171, v[68:71]
	v_mfma_f32_16x16x4_f32 v[72:75], v43, v172, v[72:75]
	v_mfma_f32_16x16x4_f32 v[76:79], v43, v173, v[76:79]
	v_mfma_f32_16x16x4_f32 v[64:67], v44, v174, v[64:67]
	v_mfma_f32_16x16x4_f32 v[68:71], v44, v175, v[68:71]
	v_mfma_f32_16x16x4_f32 v[72:75], v44, v176, v[72:75]
	v_mfma_f32_16x16x4_f32 v[76:79], v44, v177, v[76:79]
	v_mfma_f32_16x16x4_f32 v[64:67], v45, v178, v[64:67]
	v_mfma_f32_16x16x4_f32 v[68:71], v45, v179, v[68:71]
	v_mfma_f32_16x16x4_f32 v[72:75], v45, v180, v[72:75]
	v_mfma_f32_16x16x4_f32 v[76:79], v45, v181, v[76:79]
	v_mfma_f32_16x16x4_f32 v[64:67], v46, v182, v[64:67]
	v_mfma_f32_16x16x4_f32 v[68:71], v46, v183, v[68:71]
	v_mfma_f32_16x16x4_f32 v[72:75], v46, v184, v[72:75]
	v_mfma_f32_16x16x4_f32 v[76:79], v46, v185, v[76:79]
	v_mfma_f32_16x16x4_f32 v[64:67], v47, v220, v[64:67]
	v_mfma_f32_16x16x4_f32 v[68:71], v47, v221, v[68:71]
	v_mfma_f32_16x16x4_f32 v[72:75], v47, v222, v[72:75]
	v_mfma_f32_16x16x4_f32 v[76:79], v47, v223, v[76:79]
	s_waitcnt vmcnt(8)
; __device__ __forceinline__ unsigned pk2(float lo, float hi) { f32x2_t v = {lo, hi}; bf16x2_t b = __builtin_convertvector(v, bf16x2_t); return __builtin_bit_cast(unsigned, b); }
; __device__ __forceinline__ float wave_sum(float v) { v += __shfl_xor(v, 1); v += __shfl_xor(v, 2); v += __shfl_xor(v, 4); v += __shfl_xor(v, 8); v += __shfl_xor(v, 16); v += __shfl_xor(v, 32); return v; }
; __global__ void __launch_bounds__(512, 2) hybrid_fwd(Params P) {
;     ...
;                 const float* wp = cw2 + (size_t)kv * 256 * 64 + lane; float a = 0.f;
; #pragma unroll
;                 for (int k = 0; k < 256; ++k) { const float hk = __uint_as_float(__builtin_amdgcn_readlane(__float_as_uint(hv[k & 3]), k >> 2)); a = fmaf(hk, wp[k * 64], a); }
;                 if (kv == 0) { const float ss = wave_sum(a * a); float y = a * __builtin_amdgcn_rsqf(ss * (1.0f / 64.0f) + 1e-6f) * nkn[lane]; if (n == 511) y = 0.f;
;                     KC[((size_t)bg * 512 + n) * 64 + lane] = (bf16_t)(pk2(y, 0.f) & 0xffffu); }
;                 else { if (n == 511) a = 0.f; VCT[((size_t)bg * 64 + lane) * 512 + n] = (bf16_t)(pk2(a, 0.f) & 0xffffu); } }
	v_mfma_f32_16x16x4_f32 v[64:67], v48, v82, v[64:67]
	v_mfma_f32_16x16x4_f32 v[68:71], v48, v83, v[68:71]
	v_mfma_f32_16x16x4_f32 v[72:75], v48, v84, v[72:75]
	v_mfma_f32_16x16x4_f32 v[76:79], v48, v85, v[76:79]
	v_mfma_f32_16x16x4_f32 v[64:67], v49, v86, v[64:67]
	v_mfma_f32_16x16x4_f32 v[68:71], v49, v87, v[68:71]
	v_mfma_f32_16x16x4_f32 v[72:75], v49, v88, v[72:75]
	v_mfma_f32_16x16x4_f32 v[76:79], v49, v89, v[76:79]
	v_mfma_f32_16x16x4_f32 v[64:67], v50, v90, v[64:67]
	v_mfma_f32_16x16x4_f32 v[68:71], v50, v91, v[68:71]
	v_mfma_f32_16x16x4_f32 v[72:75], v50, v92, v[72:75]
	v_mfma_f32_16x16x4_f32 v[76:79], v50, v93, v[76:79]
	v_mfma_f32_16x16x4_f32 v[64:67], v51, v94, v[64:67]
	v_mfma_f32_16x16x4_f32 v[68:71], v51, v95, v[68:71]
	v_mfma_f32_16x16x4_f32 v[72:75], v51, v96, v[72:75]
	v_mfma_f32_16x16x4_f32 v[76:79], v51, v97, v[76:79]
	v_mfma_f32_16x16x4_f32 v[64:67], v52, v98, v[64:67]
	v_mfma_f32_16x16x4_f32 v[68:71], v52, v99, v[68:71]
	v_mfma_f32_16x16x4_f32 v[72:75], v52, v100, v[72:75]
	v_mfma_f32_16x16x4_f32 v[76:79], v52, v101, v[76:79]
	v_mfma_f32_16x16x4_f32 v[64:67], v53, v102, v[64:67]
	v_mfma_f32_16x16x4_f32 v[68:71], v53, v103, v[68:71]
	v_mfma_f32_16x16x4_f32 v[72:75], v53, v104, v[72:75]
	v_mfma_f32_16x16x4_f32 v[76:79], v53, v105, v[76:79]
	v_mfma_f32_16x16x4_f32 v[64:67], v54, v106, v[64:67]
	v_mfma_f32_16x16x4_f32 v[68:71], v54, v107, v[68:71]
	v_mfma_f32_16x16x4_f32 v[72:75], v54, v108, v[72:75]
	v_mfma_f32_16x16x4_f32 v[76:79], v54, v109, v[76:79]
	v_mfma_f32_16x16x4_f32 v[64:67], v55, v110, v[64:67]
	v_mfma_f32_16x16x4_f32 v[68:71], v55, v111, v[68:71]
	v_mfma_f32_16x16x4_f32 v[72:75], v55, v112, v[72:75]
	v_mfma_f32_16x16x4_f32 v[76:79], v55, v113, v[76:79]
	s_waitcnt vmcnt(0)
	v_mfma_f32_16x16x4_f32 v[64:67], v56, v114, v[64:67]
	v_mfma_f32_16x16x4_f32 v[68:71], v56, v115, v[68:71]
	v_mfma_f32_16x16x4_f32 v[72:75], v56, v116, v[72:75]
	v_mfma_f32_16x16x4_f32 v[76:79], v56, v117, v[76:79]
	v_mfma_f32_16x16x4_f32 v[64:67], v57, v118, v[64:67]
	v_mfma_f32_16x16x4_f32 v[68:71], v57, v119, v[68:71]
	v_mfma_f32_16x16x4_f32 v[72:75], v57, v120, v[72:75]
	v_mfma_f32_16x16x4_f32 v[76:79], v57, v121, v[76:79]
	v_mfma_f32_16x16x4_f32 v[64:67], v58, v122, v[64:67]
	v_mfma_f32_16x16x4_f32 v[68:71], v58, v123, v[68:71]
	v_mfma_f32_16x16x4_f32 v[72:75], v58, v124, v[72:75]
	v_mfma_f32_16x16x4_f32 v[76:79], v58, v125, v[76:79]
	v_mfma_f32_16x16x4_f32 v[64:67], v59, v126, v[64:67]
	v_mfma_f32_16x16x4_f32 v[68:71], v59, v127, v[68:71]
	v_mfma_f32_16x16x4_f32 v[72:75], v59, v128, v[72:75]
	v_mfma_f32_16x16x4_f32 v[76:79], v59, v129, v[76:79]
	v_mfma_f32_16x16x4_f32 v[64:67], v60, v130, v[64:67]
	v_mfma_f32_16x16x4_f32 v[68:71], v60, v131, v[68:71]
	v_mfma_f32_16x16x4_f32 v[72:75], v60, v132, v[72:75]
	v_mfma_f32_16x16x4_f32 v[76:79], v60, v133, v[76:79]
	v_mfma_f32_16x16x4_f32 v[64:67], v61, v134, v[64:67]
	v_mfma_f32_16x16x4_f32 v[68:71], v61, v135, v[68:71]
	v_mfma_f32_16x16x4_f32 v[72:75], v61, v136, v[72:75]
	v_mfma_f32_16x16x4_f32 v[76:79], v61, v137, v[76:79]
	v_mfma_f32_16x16x4_f32 v[64:67], v62, v138, v[64:67]
	v_mfma_f32_16x16x4_f32 v[68:71], v62, v139, v[68:71]
	v_mfma_f32_16x16x4_f32 v[72:75], v62, v140, v[72:75]
	v_mfma_f32_16x16x4_f32 v[76:79], v62, v141, v[76:79]
	v_mfma_f32_16x16x4_f32 v[64:67], v63, v142, v[64:67]
	v_mfma_f32_16x16x4_f32 v[68:71], v63, v143, v[68:71]
	v_mfma_f32_16x16x4_f32 v[72:75], v63, v144, v[72:75]
	v_mfma_f32_16x16x4_f32 v[76:79], v63, v145, v[76:79]
	s_nop 7
	s_nop 7
	v_lshl_add_u32 v253, v246, 2, s8
	v_and_b32_e32 v253, 0x1ff, v253
	v_cmp_eq_u32_e32 vcc, 0x1fc, v253
	s_mov_b64 s[18:19], vcc
	s_cmp_lg_u32 s9, 0
	s_cbranch_scc1 .Lphd_v
; __device__ __forceinline__ unsigned pk2(float lo, float hi) { f32x2_t v = {lo, hi}; bf16x2_t b = __builtin_convertvector(v, bf16x2_t); return __builtin_bit_cast(unsigned, b); }
; __device__ __forceinline__ float wave_sum(float v) { v += __shfl_xor(v, 1); v += __shfl_xor(v, 2); v += __shfl_xor(v, 4); v += __shfl_xor(v, 8); v += __shfl_xor(v, 16); v += __shfl_xor(v, 32); return v; }
; __global__ void __launch_bounds__(512, 2) hybrid_fwd(Params P) {
;     ...
;                 if (kv == 0) { const float ss = wave_sum(a * a); float y = a * __builtin_amdgcn_rsqf(ss * (1.0f / 64.0f) + 1e-6f) * nkn[lane]; if (n == 511) y = 0.f;
;                     KC[((size_t)bg * 512 + n) * 64 + lane] = (bf16_t)(pk2(y, 0.f) & 0xffffu); }
;                 else { if (n == 511) a = 0.f; VCT[((size_t)bg * 64 + lane) * 512 + n] = (bf16_t)(pk2(a, 0.f) & 0xffffu); } }
	v_mul_f32_e32 v0, v64, v64
	v_mul_f32_e32 v1, v65, v65
	v_mul_f32_e32 v2, v66, v66
	v_mul_f32_e32 v3, v67, v67
	v_fmac_f32_e32 v0, v68, v68
	v_fmac_f32_e32 v1, v69, v69
	v_fmac_f32_e32 v2, v70, v70
	v_fmac_f32_e32 v3, v71, v71
	v_fmac_f32_e32 v0, v72, v72
	v_fmac_f32_e32 v1, v73, v73
	v_fmac_f32_e32 v2, v74, v74
	v_fmac_f32_e32 v3, v75, v75
	v_fmac_f32_e32 v0, v76, v76
	v_fmac_f32_e32 v1, v77, v77
	v_fmac_f32_e32 v2, v78, v78
	v_fmac_f32_e32 v3, v79, v79
	s_nop 1
	v_add_f32_dpp v4, v0, v0 row_ror:8 row_mask:0xf bank_mask:0xf
	v_add_f32_dpp v5, v1, v1 row_ror:8 row_mask:0xf bank_mask:0xf
	v_add_f32_dpp v6, v2, v2 row_ror:8 row_mask:0xf bank_mask:0xf
	v_add_f32_dpp v7, v3, v3 row_ror:8 row_mask:0xf bank_mask:0xf
	s_nop 1
	v_mov_b32_e32 v0, v4
	v_mov_b32_e32 v1, v5
	v_mov_b32_e32 v2, v6
	v_mov_b32_e32 v3, v7
	s_nop 1
	v_add_f32_dpp v4, v0, v0 row_ror:4 row_mask:0xf bank_mask:0xf
	v_add_f32_dpp v5, v1, v1 row_ror:4 row_mask:0xf bank_mask:0xf
	v_add_f32_dpp v6, v2, v2 row_ror:4 row_mask:0xf bank_mask:0xf
	v_add_f32_dpp v7, v3, v3 row_ror:4 row_mask:0xf bank_mask:0xf
	s_nop 1
	v_mov_b32_e32 v0, v4
	v_mov_b32_e32 v1, v5
	v_mov_b32_e32 v2, v6
	v_mov_b32_e32 v3, v7
	s_nop 1
	v_add_f32_dpp v4, v0, v0 row_ror:2 row_mask:0xf bank_mask:0xf
	v_add_f32_dpp v5, v1, v1 row_ror:2 row_mask:0xf bank_mask:0xf
	v_add_f32_dpp v6, v2, v2 row_ror:2 row_mask:0xf bank_mask:0xf
	v_add_f32_dpp v7, v3, v3 row_ror:2 row_mask:0xf bank_mask:0xf
	s_nop 1
	v_mov_b32_e32 v0, v4
	v_mov_b32_e32 v1, v5
	v_mov_b32_e32 v2, v6
	v_mov_b32_e32 v3, v7
	s_nop 1
	v_add_f32_dpp v4, v0, v0 row_ror:1 row_mask:0xf bank_mask:0xf
	v_add_f32_dpp v5, v1, v1 row_ror:1 row_mask:0xf bank_mask:0xf
	v_add_f32_dpp v6, v2, v2 row_ror:1 row_mask:0xf bank_mask:0xf
	v_add_f32_dpp v7, v3, v3 row_ror:1 row_mask:0xf bank_mask:0xf
	s_nop 1
	v_mov_b32_e32 v0, v4
	v_mov_b32_e32 v1, v5
	v_mov_b32_e32 v2, v6
	v_mov_b32_e32 v3, v7
	v_fmamk_f32 v0, v0, 0x3c800000, v147
	v_fmamk_f32 v1, v1, 0x3c800000, v147
	v_fmamk_f32 v2, v2, 0x3c800000, v147
	v_fmamk_f32 v3, v3, 0x3c800000, v147
	v_rsq_f32_e32 v0, v0
	v_rsq_f32_e32 v1, v1
	v_rsq_f32_e32 v2, v2
	v_rsq_f32_e32 v3, v3
	s_nop 0
	v_mul_f32_e32 v64, v64, v0
	v_mul_f32_e32 v65, v65, v1
	v_mul_f32_e32 v66, v66, v2
	v_mul_f32_e32 v67, v67, v3
	v_mul_f32_e32 v68, v68, v0
	v_mul_f32_e32 v69, v69, v1
	v_mul_f32_e32 v70, v70, v2
	v_mul_f32_e32 v71, v71, v3
	v_mul_f32_e32 v72, v72, v0
	v_mul_f32_e32 v73, v73, v1
	v_mul_f32_e32 v74, v74, v2
	v_mul_f32_e32 v75, v75, v3
	v_mul_f32_e32 v76, v76, v0
	v_mul_f32_e32 v77, v77, v1
	v_mul_f32_e32 v78, v78, v2
	v_mul_f32_e32 v79, v79, v3
	v_mul_f32_e32 v64, v64, v240
	v_mul_f32_e32 v65, v65, v240
	v_mul_f32_e32 v66, v66, v240
	v_mul_f32_e32 v67, v67, v240
	v_mul_f32_e32 v68, v68, v241
	v_mul_f32_e32 v69, v69, v241
	v_mul_f32_e32 v70, v70, v241
	v_mul_f32_e32 v71, v71, v241
	v_mul_f32_e32 v72, v72, v242
	v_mul_f32_e32 v73, v73, v242
	v_mul_f32_e32 v74, v74, v242
	v_mul_f32_e32 v75, v75, v242
	v_mul_f32_e32 v76, v76, v243
	v_mul_f32_e32 v77, v77, v243
	v_mul_f32_e32 v78, v78, v243
	v_mul_f32_e32 v79, v79, v243
	v_cndmask_b32_e64 v67, v67, 0, s[18:19]
	v_cndmask_b32_e64 v71, v71, 0, s[18:19]
	v_cndmask_b32_e64 v75, v75, 0, s[18:19]
	v_cndmask_b32_e64 v79, v79, 0, s[18:19]
	v_cvt_pk_bf16_f32 v8, v64, v68
	v_cvt_pk_bf16_f32 v9, v72, v76
	v_cvt_pk_bf16_f32 v10, v65, v69
	v_cvt_pk_bf16_f32 v11, v73, v77
	v_cvt_pk_bf16_f32 v12, v66, v70
	v_cvt_pk_bf16_f32 v13, v74, v78
	v_cvt_pk_bf16_f32 v14, v67, v71
	v_cvt_pk_bf16_f32 v15, v75, v79
	s_lshl_b32 s16, s8, 7
	s_add_u32 s16, s16, 0x2d00000
	s_add_u32 s12, s4, s16
	s_addc_u32 s13, s5, 0
	global_store_dwordx2 v251, v[8:9], s[12:13]
	global_store_dwordx2 v251, v[10:11], s[12:13] offset:128
	global_store_dwordx2 v251, v[12:13], s[12:13] offset:256
	global_store_dwordx2 v251, v[14:15], s[12:13] offset:384
	s_branch .LBB0_784
.Lphd_v:
	v_cndmask_b32_e64 v67, v67, 0, s[18:19]
	v_cndmask_b32_e64 v71, v71, 0, s[18:19]
	v_cndmask_b32_e64 v75, v75, 0, s[18:19]
	v_cndmask_b32_e64 v79, v79, 0, s[18:19]
	v_cvt_pk_bf16_f32 v8, v64, v65
	v_cvt_pk_bf16_f32 v9, v66, v67
	v_cvt_pk_bf16_f32 v10, v68, v69
	v_cvt_pk_bf16_f32 v11, v70, v71
	v_cvt_pk_bf16_f32 v12, v72, v73
	v_cvt_pk_bf16_f32 v13, v74, v75
	v_cvt_pk_bf16_f32 v14, v76, v77
	v_cvt_pk_bf16_f32 v15, v78, v79
	s_lshr_b32 s16, s8, 9
	s_lshl_b32 s16, s16, 16
	s_and_b32 s7, s8, 0x1ff
	s_lshl_b32 s7, s7, 1
	s_add_u32 s16, s16, s7
	s_add_u32 s16, s16, 0x2d80000
	s_add_u32 s12, s4, s16
	s_addc_u32 s13, s5, 0
	global_store_dwordx2 v252, v[8:9], s[12:13]
	global_store_dwordx2 v252, v[10:11], s[12:13] offset:1024
	global_store_dwordx2 v252, v[12:13], s[12:13] offset:2048
	global_store_dwordx2 v252, v[14:15], s[12:13] offset:3072

; #define LAS __attribute__((address_space(3)))
; __device__ __forceinline__ float wave_max(float v) { v = fmaxf(v, __shfl_xor(v, 1)); v = fmaxf(v, __shfl_xor(v, 2)); v = fmaxf(v, __shfl_xor(v, 4)); v = fmaxf(v, __shfl_xor(v, 8)); v = fmaxf(v, __shfl_xor(v, 16)); v = fmaxf(v, __shfl_xor(v, 32)); return v; }
; #define INP(k) ({ int k_ = (k); LAUNDER_S(k_); (const float*)(const GAS float*)P.in[k_]; })
; __global__ void __launch_bounds__(512, 2) hybrid_fwd(Params P) {
;     ...
;         { PHASE_BEGIN
;             LAS unsigned* misc = (LAS unsigned*)(lds + ATT_MISC); LAS float* btab = (LAS float*)(lds + ATT_BT);
;             const float* rel_bias = INP(1);
;             __syncthreads();
;             if (wave == 0) { const float* mqn = INP(4) + L * 64; const float* mkn = INP(5) + L * 64; const float* nqn = INP(6) + L * 64; const float* nkn = INP(7) + L * 192;
;                 float gq = fmaxf(fabsf(mqn[lane]), fabsf(nqn[lane])); float gk = fmaxf(fmaxf(fabsf(mkn[lane]), fabsf(nkn[lane])), fmaxf(fabsf(nkn[64 + lane]), fabsf(nkn[128 + lane])));
;                 float bm = 0.f;
; #pragma unroll
;                 for (int i = 0; i < 6; ++i) bm = fmaxf(bm, fabsf(rel_bias[lane + 64 * i]));
;                 gq = wave_max(gq); gk = wave_max(gk); bm = wave_max(bm);
;                 if (lane == 0) ((LAS float*)misc)[2] = 8.0f * gq * gk + bm; }
.LBB0_794:
	s_nop 0
	s_nop 0
	s_nop 0
	s_nop 0
	s_nop 0
	s_nop 0
	s_or_b64 exec, exec, s[4:5]
	v_readlane_b32 s4, v255, 17
	s_mov_b64 s[6:7], s[58:59]
	s_mov_b32 s5, s69
	s_barrier
	s_mov_b32 s5, s2
	v_mov_b32_e32 v210, v146
	s_mov_b32 s8, 1
	s_ashr_i32 s9, s8, 31
	s_lshl_b64 s[8:9], s[8:9], 3
	s_add_u32 s8, s0, s8
	s_addc_u32 s9, s1, s9
	s_load_dwordx2 s[8:9], s[8:9], 0x0
	s_waitcnt lgkmcnt(0)
	v_lshlrev_b32_e32 v253, 2, v210
	v_cmp_gt_u32_e32 vcc, 0x180, v210
	s_and_saveexec_b64 s[98:99], vcc
	global_load_dword v252, v253, s[8:9]
	s_mov_b64 exec, s[98:99]
	s_nop 3
	v_readfirstlane_b32 s5, v210
	s_cmp_lt_u32 s5, 64
	s_waitcnt lgkmcnt(0)
	s_barrier
	s_cbranch_scc0 .LBB0_798
	s_mov_b32 s10, 4
	s_ashr_i32 s11, s10, 31
	s_lshl_b64 s[10:11], s[10:11], 3
	s_add_u32 s10, s0, s10
	s_addc_u32 s11, s1, s11
	s_load_dwordx2 s[12:13], s[10:11], 0x0
	s_lshl_b32 s10, s4, 6
	s_ashr_i32 s11, s10, 31
	s_lshl_b64 s[10:11], s[10:11], 2
	s_mov_b32 s14, 5
	s_waitcnt lgkmcnt(0)
	s_add_u32 s12, s12, s10
	s_addc_u32 s13, s13, s11
	s_ashr_i32 s15, s14, 31
	s_lshl_b64 s[14:15], s[14:15], 3
	s_add_u32 s14, s0, s14
	s_addc_u32 s15, s1, s15
	s_load_dwordx2 s[14:15], s[14:15], 0x0
	s_mov_b32 s16, 6
	v_and_b32_e32 v0, 63, v210
	v_lshlrev_b32_e32 v1, 2, v0
	s_waitcnt lgkmcnt(0)
	s_add_u32 s18, s14, s10
	s_addc_u32 s19, s15, s11
	s_ashr_i32 s17, s16, 31
	s_lshl_b64 s[14:15], s[16:17], 3
	s_add_u32 s14, s0, s14
	s_addc_u32 s15, s1, s15
	s_load_dwordx2 s[14:15], s[14:15], 0x0
	s_mov_b32 s16, 7
	global_load_dword v2, v1, s[18:19]
	global_load_dword v3, v1, s[8:9]
	global_load_dword v4, v1, s[8:9] offset:256
	global_load_dword v5, v1, s[8:9] offset:512
	global_load_dword v6, v1, s[8:9] offset:768
	global_load_dword v7, v1, s[8:9] offset:1024
	global_load_dword v8, v1, s[8:9] offset:1280
	global_load_dword v9, v1, s[12:13]
	s_mul_i32 s12, s4, 0xc0
	s_waitcnt lgkmcnt(0)
	s_add_u32 s10, s14, s10
	s_addc_u32 s11, s15, s11
	s_ashr_i32 s17, s16, 31
	global_load_dword v10, v1, s[10:11]
	s_lshl_b64 s[10:11], s[16:17], 3
	s_add_u32 s10, s0, s10
	s_addc_u32 s11, s1, s11
	s_load_dwordx2 s[10:11], s[10:11], 0x0
	s_ashr_i32 s13, s12, 31
	s_lshl_b64 s[12:13], s[12:13], 2
	v_mbcnt_hi_u32_b32 v13, -1, v167
	v_and_b32_e32 v15, 64, v13
	s_waitcnt lgkmcnt(0)
	s_add_u32 s10, s10, s12
	s_addc_u32 s11, s11, s13
	global_load_dword v11, v1, s[10:11] offset:512
	global_load_dword v12, v1, s[10:11] offset:256
	s_nop 0
	global_load_dword v1, v1, s[10:11]
	v_xor_b32_e32 v14, 1, v13
	v_add_u32_e32 v15, 64, v15
	v_cmp_lt_i32_e32 vcc, v14, v15
	v_xor_b32_e32 v16, 2, v13
	v_xor_b32_e32 v17, 4, v13
	v_cndmask_b32_e32 v14, v13, v14, vcc
	v_lshlrev_b32_e32 v14, 2, v14
	v_cmp_lt_i32_e32 vcc, v16, v15
	v_xor_b32_e32 v18, 8, v13
	v_xor_b32_e32 v19, 16, v13
	v_cndmask_b32_e32 v16, v13, v16, vcc
	v_cmp_lt_i32_e32 vcc, v17, v15
	v_xor_b32_e32 v20, 32, v13
	s_waitcnt vmcnt(9)
	v_max3_f32 v3, |v3|, 0, |v4|
	v_cndmask_b32_e32 v17, v13, v17, vcc
	s_waitcnt vmcnt(7)
	v_max3_f32 v3, v3, |v5|, |v6|
	v_cmp_lt_i32_e32 vcc, v18, v15
	s_waitcnt vmcnt(5)
	v_max3_f32 v3, v3, |v7|, |v8|
	ds_bpermute_b32 v4, v14, v3
	v_cndmask_b32_e32 v18, v13, v18, vcc
	v_cmp_lt_i32_e32 vcc, v19, v15
	s_waitcnt vmcnt(4)
	v_max_f32_e64 v6, |v9|, |v9|
	v_lshlrev_b32_e32 v5, 2, v18
	s_waitcnt lgkmcnt(0)
	v_max_f32_e32 v4, v4, v4
	v_cndmask_b32_e32 v19, v13, v19, vcc
	v_cmp_lt_i32_e32 vcc, v20, v15
	v_lshlrev_b32_e32 v15, 2, v16
	v_max_f32_e32 v3, v3, v4
	ds_bpermute_b32 v4, v15, v3
	s_waitcnt vmcnt(3)
	v_max_f32_e64 v7, |v10|, |v10|
	v_max_f32_e32 v6, v6, v7
	ds_bpermute_b32 v7, v14, v6
	v_lshlrev_b32_e32 v16, 2, v17
	s_waitcnt lgkmcnt(1)
	v_max_f32_e32 v4, v4, v4
	v_max_f32_e32 v3, v3, v4
	s_waitcnt vmcnt(2)
	v_max_f32_e64 v4, |v11|, |v11|
	s_waitcnt vmcnt(1)
	v_max_f32_e64 v10, |v12|, |v12|
	v_max_f32_e32 v4, v10, v4
	s_waitcnt vmcnt(0)
	v_max3_f32 v1, |v2|, |v1|, v4
	ds_bpermute_b32 v2, v14, v1
	s_waitcnt lgkmcnt(1)
	v_max_f32_e32 v7, v7, v7
	v_max_f32_e32 v6, v6, v7
	ds_bpermute_b32 v7, v15, v6
	ds_bpermute_b32 v11, v16, v3
	s_waitcnt lgkmcnt(2)
	v_max_f32_e32 v2, v2, v2
	v_max_f32_e32 v1, v1, v2
	ds_bpermute_b32 v2, v15, v1
	s_waitcnt lgkmcnt(2)
	v_max_f32_e32 v4, v7, v7
	v_max_f32_e32 v4, v6, v4
	s_waitcnt lgkmcnt(1)
	v_max_f32_e32 v6, v11, v11
	ds_bpermute_b32 v7, v16, v4
	s_waitcnt lgkmcnt(1)
	v_max_f32_e32 v2, v2, v2
	v_max_f32_e32 v1, v1, v2
	v_max_f32_e32 v3, v3, v6
	ds_bpermute_b32 v2, v16, v1
	ds_bpermute_b32 v6, v5, v3
	s_waitcnt lgkmcnt(2)
	v_max_f32_e32 v7, v7, v7
	v_max_f32_e32 v4, v4, v7
	ds_bpermute_b32 v7, v5, v4
	s_waitcnt lgkmcnt(2)
	v_max_f32_e32 v2, v2, v2
	s_waitcnt lgkmcnt(1)
	v_max_f32_e32 v6, v6, v6
	v_max_f32_e32 v1, v1, v2
	v_lshlrev_b32_e32 v8, 2, v19
	v_max_f32_e32 v3, v3, v6
	ds_bpermute_b32 v2, v5, v1
	ds_bpermute_b32 v6, v8, v3
	s_waitcnt lgkmcnt(2)
	v_max_f32_e32 v5, v7, v7
	v_max_f32_e32 v4, v4, v5
	v_cndmask_b32_e32 v13, v13, v20, vcc
	s_waitcnt lgkmcnt(1)
	v_max_f32_e32 v2, v2, v2
	s_waitcnt lgkmcnt(0)
	v_max_f32_e32 v5, v6, v6
	ds_bpermute_b32 v6, v8, v4
	v_max_f32_e32 v2, v1, v2
	ds_bpermute_b32 v7, v8, v2
	v_max_f32_e32 v1, v3, v5
	v_lshlrev_b32_e32 v9, 2, v13
	s_waitcnt lgkmcnt(1)
	v_max_f32_e32 v3, v6, v6
	v_max_f32_e32 v3, v4, v3
	s_waitcnt lgkmcnt(0)
	v_max_f32_e32 v4, v7, v7
	v_max_f32_e32 v2, v2, v4
	ds_bpermute_b32 v5, v9, v3
	ds_bpermute_b32 v4, v9, v2
	ds_bpermute_b32 v6, v9, v1
	v_cmp_eq_u32_e32 vcc, 0, v0
	s_and_saveexec_b64 s[10:11], vcc
	s_cbranch_execz .LBB0_797
	s_waitcnt lgkmcnt(2)
	v_max_f32_e32 v0, v5, v5
	v_max_f32_e32 v3, v3, v3
	v_max_f32_e32 v0, v3, v0
	s_waitcnt lgkmcnt(1)
	v_max_f32_e32 v3, v4, v4
	v_max_f32_e32 v2, v2, v2
	v_max_f32_e32 v2, v2, v3
	s_waitcnt lgkmcnt(0)
	v_max_f32_e32 v3, v6, v6
	v_max_f32_e32 v1, v1, v1
	v_mul_f32_e32 v0, 0x41000000, v0
	v_max_f32_e32 v1, v1, v3
	v_fmac_f32_e32 v1, v0, v2
	ds_write_b32 v165, v1 offset:50696
